# in-proj epilogue: straight-line per-class paths for all prompt tile classes (gate, pooling-input, q with rope, k with rope+decayed transpose, v transpose)
# speedup vs baseline: 1.0339x; 1.0064x over previous
.LBB0_310:
	s_add_u32 s0, s18, 0xfffc0080
	s_addc_u32 s1, s19, -1
	s_add_i32 s27, 0, 0x10000
	v_add_u32_e32 v147, s27, v139
	ds_read_b128 v[152:155], v147
	ds_read_b128 v[156:159], v147 offset:1024
	ds_read_b128 v[160:163], v147 offset:2048
	ds_read_b128 v[164:167], v147 offset:3072
	s_cmp_eq_u32 s26, 12
	s_cselect_b32 s17, s3, s1
	s_cselect_b32 s16, s13, s0
	s_cselect_b32 s1, s20, s25
	s_cselect_b32 s0, s21, s24
	v_lshl_add_u64 v[190:191], s[18:19], 0, v[142:143]
	s_add_i32 m0, s95, 0xc000
	ds_read_b128 v[168:171], v181
	ds_read_b128 v[172:175], v181 offset:1024
	ds_read_b128 v[176:179], v181 offset:2048
	ds_read_b128 v[182:185], v181 offset:3072
	ds_read_b128 v[186:189], v181 offset:4096
	ds_read_b128 v[202:205], v181 offset:5120
	ds_read_b128 v[206:209], v181 offset:6144
	ds_read_b128 v[210:213], v181 offset:7168
	global_load_lds_dwordx4 v[190:191], off
	v_lshl_add_u64 v[190:191], s[18:19], 0, v[144:145]
	s_add_i32 m0, s95, 0xe000
	s_nop 0
	global_load_lds_dwordx4 v[190:191], off
	s_waitcnt lgkmcnt(8)
	s_barrier
	s_waitcnt lgkmcnt(0)
	s_setprio 1
	s_waitcnt lgkmcnt(0)
	v_mfma_f32_16x16x32_bf16 v[124:127], v[152:155], v[168:171], v[124:127]
	v_mfma_f32_16x16x32_bf16 v[120:123], v[160:163], v[168:171], v[120:123]
	v_mfma_f32_16x16x32_bf16 v[108:111], v[152:155], v[176:179], v[108:111]
	v_mfma_f32_16x16x32_bf16 v[104:107], v[160:163], v[176:179], v[104:107]
	v_mfma_f32_16x16x32_bf16 v[92:95], v[152:155], v[186:189], v[92:95]
	v_mfma_f32_16x16x32_bf16 v[88:91], v[160:163], v[186:189], v[88:91]
	v_mfma_f32_16x16x32_bf16 v[76:79], v[152:155], v[206:209], v[76:79]
	v_mfma_f32_16x16x32_bf16 v[72:75], v[160:163], v[206:209], v[72:75]
	v_mfma_f32_16x16x32_bf16 v[124:127], v[156:159], v[172:175], v[124:127]
	v_mfma_f32_16x16x32_bf16 v[120:123], v[164:167], v[172:175], v[120:123]
	v_mfma_f32_16x16x32_bf16 v[108:111], v[156:159], v[182:185], v[108:111]
	v_mfma_f32_16x16x32_bf16 v[104:107], v[164:167], v[182:185], v[104:107]
	v_mfma_f32_16x16x32_bf16 v[92:95], v[156:159], v[202:205], v[92:95]
	v_mfma_f32_16x16x32_bf16 v[88:91], v[164:167], v[202:205], v[88:91]
	v_mfma_f32_16x16x32_bf16 v[76:79], v[156:159], v[210:213], v[76:79]
	v_mfma_f32_16x16x32_bf16 v[72:75], v[164:167], v[210:213], v[72:75]
	s_setprio 0
	s_barrier
	s_add_i32 s36, 0, 0x14000
	s_add_i32 s27, s27, s94
	v_add_u32_e32 v147, s36, v139
	v_lshl_add_u64 v[190:191], s[0:1], 0, v[132:133]
	s_mov_b32 m0, s27
	ds_read_b128 v[214:217], v147
	ds_read_b128 v[218:221], v147 offset:1024
	ds_read_b128 v[238:241], v147 offset:2048
	ds_read_b128 v[242:245], v147 offset:3072
	global_load_lds_dwordx4 v[190:191], off
	v_lshl_add_u64 v[222:223], s[0:1], 0, v[128:129]
	s_add_i32 m0, s27, 0x2000
	s_nop 0
	global_load_lds_dwordx4 v[222:223], off
	s_barrier
	s_waitcnt lgkmcnt(0)
	s_setprio 1
	s_waitcnt lgkmcnt(0)
	v_mfma_f32_16x16x32_bf16 v[116:119], v[214:217], v[168:171], v[116:119]
	v_mfma_f32_16x16x32_bf16 v[112:115], v[238:241], v[168:171], v[112:115]
	v_mfma_f32_16x16x32_bf16 v[100:103], v[214:217], v[176:179], v[100:103]
	v_mfma_f32_16x16x32_bf16 v[96:99], v[238:241], v[176:179], v[96:99]
	v_mfma_f32_16x16x32_bf16 v[84:87], v[214:217], v[186:189], v[84:87]
	v_mfma_f32_16x16x32_bf16 v[80:83], v[238:241], v[186:189], v[80:83]
	v_mfma_f32_16x16x32_bf16 v[68:71], v[214:217], v[206:209], v[68:71]
	v_mfma_f32_16x16x32_bf16 v[64:67], v[238:241], v[206:209], v[64:67]
	v_mfma_f32_16x16x32_bf16 v[116:119], v[218:221], v[172:175], v[116:119]
	v_mfma_f32_16x16x32_bf16 v[112:115], v[242:245], v[172:175], v[112:115]
	v_mfma_f32_16x16x32_bf16 v[100:103], v[218:221], v[182:185], v[100:103]
	v_mfma_f32_16x16x32_bf16 v[96:99], v[242:245], v[182:185], v[96:99]
	v_mfma_f32_16x16x32_bf16 v[84:87], v[218:221], v[202:205], v[84:87]
	v_mfma_f32_16x16x32_bf16 v[80:83], v[242:245], v[202:205], v[80:83]
	v_mfma_f32_16x16x32_bf16 v[68:71], v[218:221], v[210:213], v[68:71]
	v_mfma_f32_16x16x32_bf16 v[64:67], v[242:245], v[210:213], v[64:67]
	s_setprio 0
	s_mov_b32 m0, s95
	v_lshl_add_u64 v[246:247], s[16:17], 0, v[134:135]
	s_barrier
	ds_read_b128 v[168:171], v181 offset:16384
	ds_read_b128 v[172:175], v181 offset:17408
	ds_read_b128 v[176:179], v181 offset:18432
	ds_read_b128 v[182:185], v181 offset:19456
	ds_read_b128 v[186:189], v181 offset:20480
	ds_read_b128 v[202:205], v181 offset:21504
	ds_read_b128 v[206:209], v181 offset:22528
	ds_read_b128 v[210:213], v181 offset:23552
	global_load_lds_dwordx4 v[246:247], off
	v_lshl_add_u64 v[248:249], s[16:17], 0, v[130:131]
	s_mov_b32 m0, s96
	s_nop 0
	global_load_lds_dwordx4 v[248:249], off
	s_barrier
	s_waitcnt lgkmcnt(0)
	s_setprio 1
	s_waitcnt lgkmcnt(0)
	v_mfma_f32_16x16x32_bf16 v[60:63], v[152:155], v[168:171], v[60:63]
	v_mfma_f32_16x16x32_bf16 v[56:59], v[160:163], v[168:171], v[56:59]
	v_mfma_f32_16x16x32_bf16 v[44:47], v[152:155], v[176:179], v[44:47]
	v_mfma_f32_16x16x32_bf16 v[40:43], v[160:163], v[176:179], v[40:43]
	v_mfma_f32_16x16x32_bf16 v[28:31], v[152:155], v[186:189], v[28:31]
	v_mfma_f32_16x16x32_bf16 v[24:27], v[160:163], v[186:189], v[24:27]
	v_mfma_f32_16x16x32_bf16 v[12:15], v[152:155], v[206:209], v[12:15]
	v_mfma_f32_16x16x32_bf16 v[8:11], v[160:163], v[206:209], v[8:11]
	v_mfma_f32_16x16x32_bf16 v[60:63], v[156:159], v[172:175], v[60:63]
	v_mfma_f32_16x16x32_bf16 v[56:59], v[164:167], v[172:175], v[56:59]
	v_mfma_f32_16x16x32_bf16 v[44:47], v[156:159], v[182:185], v[44:47]
	v_mfma_f32_16x16x32_bf16 v[40:43], v[164:167], v[182:185], v[40:43]
	v_mfma_f32_16x16x32_bf16 v[28:31], v[156:159], v[202:205], v[28:31]
	v_mfma_f32_16x16x32_bf16 v[24:27], v[164:167], v[202:205], v[24:27]
	v_mfma_f32_16x16x32_bf16 v[12:15], v[156:159], v[210:213], v[12:15]
	v_mfma_f32_16x16x32_bf16 v[8:11], v[164:167], v[210:213], v[8:11]
	s_setprio 0
	s_barrier
	s_add_u32 s28, s0, 0x40000
	s_addc_u32 s29, s1, 0
	s_add_i32 s27, s36, s94
	v_lshl_add_u64 v[152:153], s[28:29], 0, v[132:133]
	s_mov_b32 m0, s27
	s_nop 0
	global_load_lds_dwordx4 v[152:153], off
	v_lshl_add_u64 v[152:153], s[28:29], 0, v[128:129]
	s_add_i32 m0, s27, 0x2000
	s_nop 0
	global_load_lds_dwordx4 v[152:153], off
	s_waitcnt vmcnt(6)
	s_barrier
	s_setprio 1
	v_mfma_f32_16x16x32_bf16 v[52:55], v[214:217], v[168:171], v[52:55]
	v_mfma_f32_16x16x32_bf16 v[48:51], v[238:241], v[168:171], v[48:51]
	v_mfma_f32_16x16x32_bf16 v[36:39], v[214:217], v[176:179], v[36:39]
	v_mfma_f32_16x16x32_bf16 v[32:35], v[238:241], v[176:179], v[32:35]
	v_mfma_f32_16x16x32_bf16 v[20:23], v[214:217], v[186:189], v[20:23]
	v_mfma_f32_16x16x32_bf16 v[16:19], v[238:241], v[186:189], v[16:19]
	v_mfma_f32_16x16x32_bf16 v[4:7], v[214:217], v[206:209], v[4:7]
	v_mfma_f32_16x16x32_bf16 v[0:3], v[238:241], v[206:209], v[0:3]
	v_mfma_f32_16x16x32_bf16 v[52:55], v[218:221], v[172:175], v[52:55]
	v_mfma_f32_16x16x32_bf16 v[48:51], v[242:245], v[172:175], v[48:51]
	v_mfma_f32_16x16x32_bf16 v[36:39], v[218:221], v[182:185], v[36:39]
	v_mfma_f32_16x16x32_bf16 v[32:35], v[242:245], v[182:185], v[32:35]
	v_mfma_f32_16x16x32_bf16 v[20:23], v[218:221], v[202:205], v[20:23]
	v_mfma_f32_16x16x32_bf16 v[16:19], v[242:245], v[202:205], v[16:19]
	v_mfma_f32_16x16x32_bf16 v[4:7], v[218:221], v[210:213], v[4:7]
	v_mfma_f32_16x16x32_bf16 v[0:3], v[242:245], v[210:213], v[0:3]
	s_setprio 0
	s_add_i32 s27, 0, 0x18000
	v_add_u32_e32 v147, s27, v139
	s_barrier
	ds_read_b128 v[152:155], v147
	ds_read_b128 v[156:159], v147 offset:1024
	ds_read_b128 v[160:163], v147 offset:2048
	ds_read_b128 v[164:167], v147 offset:3072
	s_add_u32 s16, s16, 0x40000
	s_addc_u32 s17, s17, 0
	s_mov_b32 m0, s97
	v_lshl_add_u64 v[214:215], s[16:17], 0, v[134:135]
	ds_read_b128 v[168:171], v181 offset:32768
	ds_read_b128 v[172:175], v181 offset:33792
	ds_read_b128 v[176:179], v181 offset:34816
	ds_read_b128 v[182:185], v181 offset:35840
	ds_read_b128 v[186:189], v181 offset:36864
	ds_read_b128 v[202:205], v181 offset:37888
	ds_read_b128 v[206:209], v181 offset:38912
	ds_read_b128 v[210:213], v181 offset:39936
	global_load_lds_dwordx4 v[214:215], off
	v_lshl_add_u64 v[214:215], s[16:17], 0, v[130:131]
	s_mov_b32 m0, s4
	s_nop 0
	global_load_lds_dwordx4 v[214:215], off
	s_waitcnt lgkmcnt(8)
	s_barrier
	s_waitcnt lgkmcnt(0)
	s_setprio 1
	s_waitcnt lgkmcnt(0)
	v_mfma_f32_16x16x32_bf16 v[124:127], v[152:155], v[168:171], v[124:127]
	v_mfma_f32_16x16x32_bf16 v[120:123], v[160:163], v[168:171], v[120:123]
	v_mfma_f32_16x16x32_bf16 v[108:111], v[152:155], v[176:179], v[108:111]
	v_mfma_f32_16x16x32_bf16 v[104:107], v[160:163], v[176:179], v[104:107]
	v_mfma_f32_16x16x32_bf16 v[92:95], v[152:155], v[186:189], v[92:95]
	v_mfma_f32_16x16x32_bf16 v[88:91], v[160:163], v[186:189], v[88:91]
	v_mfma_f32_16x16x32_bf16 v[76:79], v[152:155], v[206:209], v[76:79]
	v_mfma_f32_16x16x32_bf16 v[72:75], v[160:163], v[206:209], v[72:75]
	v_mfma_f32_16x16x32_bf16 v[124:127], v[156:159], v[172:175], v[124:127]
	v_mfma_f32_16x16x32_bf16 v[120:123], v[164:167], v[172:175], v[120:123]
	v_mfma_f32_16x16x32_bf16 v[108:111], v[156:159], v[182:185], v[108:111]
	v_mfma_f32_16x16x32_bf16 v[104:107], v[164:167], v[182:185], v[104:107]
	v_mfma_f32_16x16x32_bf16 v[92:95], v[156:159], v[202:205], v[92:95]
	v_mfma_f32_16x16x32_bf16 v[88:91], v[164:167], v[202:205], v[88:91]
	v_mfma_f32_16x16x32_bf16 v[76:79], v[156:159], v[210:213], v[76:79]
	v_mfma_f32_16x16x32_bf16 v[72:75], v[164:167], v[210:213], v[72:75]
	s_setprio 0
	s_barrier
	s_add_i32 s16, 0, 0x1c000
	s_add_i32 s17, s27, s94
	v_add_u32_e32 v147, s16, v139
	v_lshl_add_u64 v[190:191], v[190:191], 0, s[30:31]
	s_mov_b32 m0, s17
	ds_read_b128 v[214:217], v147
	ds_read_b128 v[218:221], v147 offset:1024
	ds_read_b128 v[238:241], v147 offset:2048
	ds_read_b128 v[242:245], v147 offset:3072
	global_load_lds_dwordx4 v[190:191], off
	v_lshl_add_u64 v[190:191], v[222:223], 0, s[30:31]
	s_add_i32 m0, s17, 0x2000
	s_nop 0
	global_load_lds_dwordx4 v[190:191], off
	s_barrier
	s_waitcnt lgkmcnt(0)
	s_setprio 1
	s_waitcnt lgkmcnt(0)
	v_mfma_f32_16x16x32_bf16 v[116:119], v[214:217], v[168:171], v[116:119]
	v_mfma_f32_16x16x32_bf16 v[112:115], v[238:241], v[168:171], v[112:115]
	v_mfma_f32_16x16x32_bf16 v[100:103], v[214:217], v[176:179], v[100:103]
	v_mfma_f32_16x16x32_bf16 v[96:99], v[238:241], v[176:179], v[96:99]
	v_mfma_f32_16x16x32_bf16 v[84:87], v[214:217], v[186:189], v[84:87]
	v_mfma_f32_16x16x32_bf16 v[80:83], v[238:241], v[186:189], v[80:83]
	v_mfma_f32_16x16x32_bf16 v[68:71], v[214:217], v[206:209], v[68:71]
	v_mfma_f32_16x16x32_bf16 v[64:67], v[238:241], v[206:209], v[64:67]
	v_mfma_f32_16x16x32_bf16 v[116:119], v[218:221], v[172:175], v[116:119]
	v_mfma_f32_16x16x32_bf16 v[112:115], v[242:245], v[172:175], v[112:115]
	v_mfma_f32_16x16x32_bf16 v[100:103], v[218:221], v[182:185], v[100:103]
	v_mfma_f32_16x16x32_bf16 v[96:99], v[242:245], v[182:185], v[96:99]
	v_mfma_f32_16x16x32_bf16 v[84:87], v[218:221], v[202:205], v[84:87]
	v_mfma_f32_16x16x32_bf16 v[80:83], v[242:245], v[202:205], v[80:83]
	v_mfma_f32_16x16x32_bf16 v[68:71], v[218:221], v[210:213], v[68:71]
	v_mfma_f32_16x16x32_bf16 v[64:67], v[242:245], v[210:213], v[64:67]
	s_setprio 0
	s_mov_b32 m0, s6
	v_lshl_add_u64 v[190:191], v[246:247], 0, s[30:31]
	s_barrier
	ds_read_b128 v[168:171], v181 offset:49152
	ds_read_b128 v[172:175], v181 offset:50176
	ds_read_b128 v[176:179], v181 offset:51200
	ds_read_b128 v[182:185], v181 offset:52224
	ds_read_b128 v[186:189], v181 offset:53248
	ds_read_b128 v[202:205], v181 offset:54272
	ds_read_b128 v[206:209], v181 offset:55296
	ds_read_b128 v[210:213], v181 offset:56320
	global_load_lds_dwordx4 v[190:191], off
	v_lshl_add_u64 v[190:191], v[248:249], 0, s[30:31]
	s_mov_b32 m0, s7
	s_nop 0
	global_load_lds_dwordx4 v[190:191], off
	s_barrier
	s_waitcnt lgkmcnt(0)
	s_setprio 1
	s_waitcnt lgkmcnt(0)
	v_mfma_f32_16x16x32_bf16 v[60:63], v[152:155], v[168:171], v[60:63]
	v_mfma_f32_16x16x32_bf16 v[56:59], v[160:163], v[168:171], v[56:59]
	v_mfma_f32_16x16x32_bf16 v[44:47], v[152:155], v[176:179], v[44:47]
	v_mfma_f32_16x16x32_bf16 v[40:43], v[160:163], v[176:179], v[40:43]
	v_mfma_f32_16x16x32_bf16 v[28:31], v[152:155], v[186:189], v[28:31]
	v_mfma_f32_16x16x32_bf16 v[24:27], v[160:163], v[186:189], v[24:27]
	v_mfma_f32_16x16x32_bf16 v[12:15], v[152:155], v[206:209], v[12:15]
	v_mfma_f32_16x16x32_bf16 v[8:11], v[160:163], v[206:209], v[8:11]
	v_mfma_f32_16x16x32_bf16 v[60:63], v[156:159], v[172:175], v[60:63]
	v_mfma_f32_16x16x32_bf16 v[56:59], v[164:167], v[172:175], v[56:59]
	v_mfma_f32_16x16x32_bf16 v[44:47], v[156:159], v[182:185], v[44:47]
	v_mfma_f32_16x16x32_bf16 v[40:43], v[164:167], v[182:185], v[40:43]
	v_mfma_f32_16x16x32_bf16 v[28:31], v[156:159], v[202:205], v[28:31]
	v_mfma_f32_16x16x32_bf16 v[24:27], v[164:167], v[202:205], v[24:27]
	v_mfma_f32_16x16x32_bf16 v[12:15], v[156:159], v[210:213], v[12:15]
	v_mfma_f32_16x16x32_bf16 v[8:11], v[164:167], v[210:213], v[8:11]
	s_setprio 0
	s_barrier
	s_add_u32 s0, s0, 0x40080
	s_addc_u32 s1, s1, 0
	s_add_i32 s16, s16, s94
	v_lshl_add_u64 v[152:153], s[0:1], 0, v[132:133]
	s_mov_b32 m0, s16
	s_nop 0
	global_load_lds_dwordx4 v[152:153], off
	v_lshl_add_u64 v[152:153], s[0:1], 0, v[128:129]
	s_add_i32 m0, s16, 0x2000
	s_nop 0
	global_load_lds_dwordx4 v[152:153], off
	s_waitcnt vmcnt(6)
	s_barrier
	s_setprio 1
	v_mfma_f32_16x16x32_bf16 v[52:55], v[214:217], v[168:171], v[52:55]
	v_mfma_f32_16x16x32_bf16 v[48:51], v[238:241], v[168:171], v[48:51]
	v_mfma_f32_16x16x32_bf16 v[36:39], v[214:217], v[176:179], v[36:39]
	v_mfma_f32_16x16x32_bf16 v[32:35], v[238:241], v[176:179], v[32:35]
	v_mfma_f32_16x16x32_bf16 v[20:23], v[214:217], v[186:189], v[20:23]
	v_mfma_f32_16x16x32_bf16 v[16:19], v[238:241], v[186:189], v[16:19]
	v_mfma_f32_16x16x32_bf16 v[4:7], v[214:217], v[206:209], v[4:7]
	v_mfma_f32_16x16x32_bf16 v[0:3], v[238:241], v[206:209], v[0:3]
	v_mfma_f32_16x16x32_bf16 v[52:55], v[218:221], v[172:175], v[52:55]
	v_mfma_f32_16x16x32_bf16 v[48:51], v[242:245], v[172:175], v[48:51]
	v_mfma_f32_16x16x32_bf16 v[36:39], v[218:221], v[182:185], v[36:39]
	v_mfma_f32_16x16x32_bf16 v[32:35], v[242:245], v[182:185], v[32:35]
	v_mfma_f32_16x16x32_bf16 v[20:23], v[218:221], v[202:205], v[20:23]
	v_mfma_f32_16x16x32_bf16 v[16:19], v[242:245], v[202:205], v[16:19]
	v_mfma_f32_16x16x32_bf16 v[4:7], v[218:221], v[210:213], v[4:7]
	v_mfma_f32_16x16x32_bf16 v[0:3], v[242:245], v[210:213], v[0:3]
	s_setprio 0
	s_add_i32 s26, s26, 2
	s_add_u32 s18, s18, 0x100
	s_addc_u32 s19, s19, 0
	s_add_u32 s24, s24, 0x100
	s_addc_u32 s25, s25, 0
	s_cmp_gt_u32 s26, 13
	s_barrier
	s_cbranch_scc0 .LBB0_310
	s_cmp_gt_u32 s33, 7
	s_cbranch_scc1 .Lepi_g
	s_cmp_lt_u32 s33, 2
	s_cbranch_scc1 .Lepi_u
	s_and_b32 s16, s33, -2
	s_cmp_eq_u32 s16, 6
	s_cbranch_scc1 .Lepi_v
	s_and_b32 s16, s33, -2
	s_cmp_eq_u32 s16, 2
	s_cbranch_scc1 .Lepi_q
	s_and_b32 s16, s33, -2
	s_cmp_eq_u32 s16, 4
	s_cbranch_scc1 .Lepi_k
	s_branch .Lepi_generic

.Lepi_q:
	s_lshl_b32 s16, s2, 18
	s_and_b32 s17, s33, 1
	s_lshl_b32 s17, s17, 13
	s_add_i32 s16, s16, s17
	s_add_u32 s16, s66, s16
	s_addc_u32 s17, s67, 0
	s_add_u32 s16, s16, 0x1a801000
	s_addc_u32 s17, s17, 0
	s_and_b32 s18, s2, 7
	s_lshl_b32 s18, s18, 16
	s_add_u32 s18, s66, s18
	s_addc_u32 s19, s67, 0
	s_add_u32 s18, s18, 0x4500000
	s_addc_u32 s19, s19, 0
	s_add_u32 s20, s18, 0x80800
	s_addc_u32 s21, s19, 0
	v_and_b32_e32 v246, 15, v224
	v_lshrrev_b32_e32 v249, 8, v224
	v_lshl_or_b32 v247, v249, 6, v246
	v_lshlrev_b32_e32 v247, 8, v247
	v_bfe_u32 v250, v224, 4, 4
	v_lshl_or_b32 v247, v250, 4, v247
	v_lshlrev_b32_e32 v246, 4, v246
	v_lshl_or_b32 v246, v249, 16, v246
	v_bfe_u32 v249, v224, 4, 1
	v_lshl_or_b32 v246, v249, 3, v246
	v_bfe_u32 v249, v224, 7, 1
	v_lshl_or_b32 v246, v249, 10, v246
	v_bfe_u32 v249, v224, 5, 3
	v_and_b32_e32 v249, 3, v249
	v_lshl_or_b32 v246, v249, 8, v246
	v_mov_b32_e32 v248, v247
	global_load_dwordx4 v[152:155], v248, s[18:19]
	global_load_dwordx4 v[156:159], v248, s[20:21]
	v_add_u32_e32 v248, 0x1000, v247
	global_load_dwordx4 v[160:163], v248, s[18:19]
	global_load_dwordx4 v[164:167], v248, s[20:21]
	v_add_u32_e32 v248, 0x2000, v247
	global_load_dwordx4 v[168:171], v248, s[18:19]
	global_load_dwordx4 v[172:175], v248, s[20:21]
	v_add_u32_e32 v248, 0x3000, v247
	global_load_dwordx4 v[176:179], v248, s[18:19]
	global_load_dwordx4 v[202:205], v248, s[20:21]
	v_add_u32_e32 v248, 0x8000, v247
	global_load_dwordx4 v[206:209], v248, s[18:19]
	global_load_dwordx4 v[210:213], v248, s[20:21]
	v_add_u32_e32 v248, 0x9000, v247
	global_load_dwordx4 v[214:217], v248, s[18:19]
	global_load_dwordx4 v[218:221], v248, s[20:21]
	s_waitcnt vmcnt(10)
	v_pk_mul_f32 v[238:239], v[120:121], v[156:157]
	v_pk_mul_f32 v[240:241], v[122:123], v[158:159]
	v_pk_mul_f32 v[242:243], v[124:125], v[156:157]
	v_pk_mul_f32 v[244:245], v[126:127], v[158:159]
	v_pk_fma_f32 v[124:125], v[124:125], v[152:153], v[238:239] neg_lo:[0,0,1] neg_hi:[0,0,1]
	v_pk_fma_f32 v[126:127], v[126:127], v[154:155], v[240:241] neg_lo:[0,0,1] neg_hi:[0,0,1]
	v_pk_fma_f32 v[120:121], v[120:121], v[152:153], v[242:243]
	v_pk_fma_f32 v[122:123], v[122:123], v[154:155], v[244:245]
	v_mov_b32_e32 v251, v246
	v_cvt_pk_bf16_f32 v238, v124, v125
	v_cvt_pk_bf16_f32 v239, v126, v127
	v_cvt_pk_bf16_f32 v240, v120, v121
	v_cvt_pk_bf16_f32 v241, v122, v123
	global_store_dwordx2 v251, v[238:239], s[16:17]
	global_store_dwordx2 v251, v[240:241], s[16:17] offset:2048
	v_pk_mul_f32 v[238:239], v[112:113], v[156:157]
	v_pk_mul_f32 v[240:241], v[114:115], v[158:159]
	v_pk_mul_f32 v[242:243], v[116:117], v[156:157]
	v_pk_mul_f32 v[244:245], v[118:119], v[158:159]
	v_pk_fma_f32 v[116:117], v[116:117], v[152:153], v[238:239] neg_lo:[0,0,1] neg_hi:[0,0,1]
	v_pk_fma_f32 v[118:119], v[118:119], v[154:155], v[240:241] neg_lo:[0,0,1] neg_hi:[0,0,1]
	v_pk_fma_f32 v[112:113], v[112:113], v[152:153], v[242:243]
	v_pk_fma_f32 v[114:115], v[114:115], v[154:155], v[244:245]
	v_add_u32_e32 v252, 0x1000, v246
	v_cvt_pk_bf16_f32 v242, v116, v117
	v_cvt_pk_bf16_f32 v243, v118, v119
	v_cvt_pk_bf16_f32 v244, v112, v113
	v_cvt_pk_bf16_f32 v245, v114, v115
	global_store_dwordx2 v252, v[242:243], s[16:17]
	global_store_dwordx2 v252, v[244:245], s[16:17] offset:2048
	s_waitcnt vmcnt(12)
	v_pk_mul_f32 v[238:239], v[104:105], v[164:165]
	v_pk_mul_f32 v[240:241], v[106:107], v[166:167]
	v_pk_mul_f32 v[242:243], v[108:109], v[164:165]
	v_pk_mul_f32 v[244:245], v[110:111], v[166:167]
	v_pk_fma_f32 v[108:109], v[108:109], v[160:161], v[238:239] neg_lo:[0,0,1] neg_hi:[0,0,1]
	v_pk_fma_f32 v[110:111], v[110:111], v[162:163], v[240:241] neg_lo:[0,0,1] neg_hi:[0,0,1]
	v_pk_fma_f32 v[104:105], v[104:105], v[160:161], v[242:243]
	v_pk_fma_f32 v[106:107], v[106:107], v[162:163], v[244:245]
	v_add_u32_e32 v251, 0x4000, v246
	v_cvt_pk_bf16_f32 v238, v108, v109
	v_cvt_pk_bf16_f32 v239, v110, v111
	v_cvt_pk_bf16_f32 v240, v104, v105
	v_cvt_pk_bf16_f32 v241, v106, v107
	global_store_dwordx2 v251, v[238:239], s[16:17]
	global_store_dwordx2 v251, v[240:241], s[16:17] offset:2048
	v_pk_mul_f32 v[238:239], v[96:97], v[164:165]
	v_pk_mul_f32 v[240:241], v[98:99], v[166:167]
	v_pk_mul_f32 v[242:243], v[100:101], v[164:165]
	v_pk_mul_f32 v[244:245], v[102:103], v[166:167]
	v_pk_fma_f32 v[100:101], v[100:101], v[160:161], v[238:239] neg_lo:[0,0,1] neg_hi:[0,0,1]
	v_pk_fma_f32 v[102:103], v[102:103], v[162:163], v[240:241] neg_lo:[0,0,1] neg_hi:[0,0,1]
	v_pk_fma_f32 v[96:97], v[96:97], v[160:161], v[242:243]
	v_pk_fma_f32 v[98:99], v[98:99], v[162:163], v[244:245]
	v_add_u32_e32 v252, 0x5000, v246
	v_cvt_pk_bf16_f32 v242, v100, v101
	v_cvt_pk_bf16_f32 v243, v102, v103
	v_cvt_pk_bf16_f32 v244, v96, v97
	v_cvt_pk_bf16_f32 v245, v98, v99
	global_store_dwordx2 v252, v[242:243], s[16:17]
	global_store_dwordx2 v252, v[244:245], s[16:17] offset:2048
	v_add_u32_e32 v248, 0xa000, v247
	global_load_dwordx4 v[152:155], v248, s[18:19]
	global_load_dwordx4 v[156:159], v248, s[20:21]
	v_add_u32_e32 v248, 0xb000, v247
	global_load_dwordx4 v[160:163], v248, s[18:19]
	global_load_dwordx4 v[164:167], v248, s[20:21]
	s_waitcnt vmcnt(18)
	v_pk_mul_f32 v[238:239], v[88:89], v[172:173]
	v_pk_mul_f32 v[240:241], v[90:91], v[174:175]
	v_pk_mul_f32 v[242:243], v[92:93], v[172:173]
	v_pk_mul_f32 v[244:245], v[94:95], v[174:175]
	v_pk_fma_f32 v[92:93], v[92:93], v[168:169], v[238:239] neg_lo:[0,0,1] neg_hi:[0,0,1]
	v_pk_fma_f32 v[94:95], v[94:95], v[170:171], v[240:241] neg_lo:[0,0,1] neg_hi:[0,0,1]
	v_pk_fma_f32 v[88:89], v[88:89], v[168:169], v[242:243]
	v_pk_fma_f32 v[90:91], v[90:91], v[170:171], v[244:245]
	v_add_u32_e32 v251, 0x8000, v246
	v_cvt_pk_bf16_f32 v238, v92, v93
	v_cvt_pk_bf16_f32 v239, v94, v95
	v_cvt_pk_bf16_f32 v240, v88, v89
	v_cvt_pk_bf16_f32 v241, v90, v91
	global_store_dwordx2 v251, v[238:239], s[16:17]
	global_store_dwordx2 v251, v[240:241], s[16:17] offset:2048
	v_pk_mul_f32 v[238:239], v[80:81], v[172:173]
	v_pk_mul_f32 v[240:241], v[82:83], v[174:175]
	v_pk_mul_f32 v[242:243], v[84:85], v[172:173]
	v_pk_mul_f32 v[244:245], v[86:87], v[174:175]
	v_pk_fma_f32 v[84:85], v[84:85], v[168:169], v[238:239] neg_lo:[0,0,1] neg_hi:[0,0,1]
	v_pk_fma_f32 v[86:87], v[86:87], v[170:171], v[240:241] neg_lo:[0,0,1] neg_hi:[0,0,1]
	v_pk_fma_f32 v[80:81], v[80:81], v[168:169], v[242:243]
	v_pk_fma_f32 v[82:83], v[82:83], v[170:171], v[244:245]
	v_add_u32_e32 v252, 0x9000, v246
	v_cvt_pk_bf16_f32 v242, v84, v85
	v_cvt_pk_bf16_f32 v243, v86, v87
	v_cvt_pk_bf16_f32 v244, v80, v81
	v_cvt_pk_bf16_f32 v245, v82, v83
	global_store_dwordx2 v252, v[242:243], s[16:17]
	global_store_dwordx2 v252, v[244:245], s[16:17] offset:2048
	s_waitcnt vmcnt(20)
	v_pk_mul_f32 v[238:239], v[72:73], v[202:203]
	v_pk_mul_f32 v[240:241], v[74:75], v[204:205]
	v_pk_mul_f32 v[242:243], v[76:77], v[202:203]
	v_pk_mul_f32 v[244:245], v[78:79], v[204:205]
	v_pk_fma_f32 v[76:77], v[76:77], v[176:177], v[238:239] neg_lo:[0,0,1] neg_hi:[0,0,1]
	v_pk_fma_f32 v[78:79], v[78:79], v[178:179], v[240:241] neg_lo:[0,0,1] neg_hi:[0,0,1]
	v_pk_fma_f32 v[72:73], v[72:73], v[176:177], v[242:243]
	v_pk_fma_f32 v[74:75], v[74:75], v[178:179], v[244:245]
	v_add_u32_e32 v251, 0xc000, v246
	v_cvt_pk_bf16_f32 v238, v76, v77
	v_cvt_pk_bf16_f32 v239, v78, v79
	v_cvt_pk_bf16_f32 v240, v72, v73
	v_cvt_pk_bf16_f32 v241, v74, v75
	global_store_dwordx2 v251, v[238:239], s[16:17]
	global_store_dwordx2 v251, v[240:241], s[16:17] offset:2048
	v_pk_mul_f32 v[238:239], v[64:65], v[202:203]
	v_pk_mul_f32 v[240:241], v[66:67], v[204:205]
	v_pk_mul_f32 v[242:243], v[68:69], v[202:203]
	v_pk_mul_f32 v[244:245], v[70:71], v[204:205]
	v_pk_fma_f32 v[68:69], v[68:69], v[176:177], v[238:239] neg_lo:[0,0,1] neg_hi:[0,0,1]
	v_pk_fma_f32 v[70:71], v[70:71], v[178:179], v[240:241] neg_lo:[0,0,1] neg_hi:[0,0,1]
	v_pk_fma_f32 v[64:65], v[64:65], v[176:177], v[242:243]
	v_pk_fma_f32 v[66:67], v[66:67], v[178:179], v[244:245]
	v_add_u32_e32 v252, 0xd000, v246
	v_cvt_pk_bf16_f32 v242, v68, v69
	v_cvt_pk_bf16_f32 v243, v70, v71
	v_cvt_pk_bf16_f32 v244, v64, v65
	v_cvt_pk_bf16_f32 v245, v66, v67
	global_store_dwordx2 v252, v[242:243], s[16:17]
	global_store_dwordx2 v252, v[244:245], s[16:17] offset:2048
	s_waitcnt vmcnt(22)
	v_pk_mul_f32 v[238:239], v[56:57], v[210:211]
	v_pk_mul_f32 v[240:241], v[58:59], v[212:213]
	v_pk_mul_f32 v[242:243], v[60:61], v[210:211]
	v_pk_mul_f32 v[244:245], v[62:63], v[212:213]
	v_pk_fma_f32 v[60:61], v[60:61], v[206:207], v[238:239] neg_lo:[0,0,1] neg_hi:[0,0,1]
	v_pk_fma_f32 v[62:63], v[62:63], v[208:209], v[240:241] neg_lo:[0,0,1] neg_hi:[0,0,1]
	v_pk_fma_f32 v[56:57], v[56:57], v[206:207], v[242:243]
	v_pk_fma_f32 v[58:59], v[58:59], v[208:209], v[244:245]
	v_add_u32_e32 v251, 0x20000, v246
	v_cvt_pk_bf16_f32 v238, v60, v61
	v_cvt_pk_bf16_f32 v239, v62, v63
	v_cvt_pk_bf16_f32 v240, v56, v57
	v_cvt_pk_bf16_f32 v241, v58, v59
	global_store_dwordx2 v251, v[238:239], s[16:17]
	global_store_dwordx2 v251, v[240:241], s[16:17] offset:2048
	v_pk_mul_f32 v[238:239], v[48:49], v[210:211]
	v_pk_mul_f32 v[240:241], v[50:51], v[212:213]
	v_pk_mul_f32 v[242:243], v[52:53], v[210:211]
	v_pk_mul_f32 v[244:245], v[54:55], v[212:213]
	v_pk_fma_f32 v[52:53], v[52:53], v[206:207], v[238:239] neg_lo:[0,0,1] neg_hi:[0,0,1]
	v_pk_fma_f32 v[54:55], v[54:55], v[208:209], v[240:241] neg_lo:[0,0,1] neg_hi:[0,0,1]
	v_pk_fma_f32 v[48:49], v[48:49], v[206:207], v[242:243]
	v_pk_fma_f32 v[50:51], v[50:51], v[208:209], v[244:245]
	v_add_u32_e32 v252, 0x21000, v246
	v_cvt_pk_bf16_f32 v242, v52, v53
	v_cvt_pk_bf16_f32 v243, v54, v55
	v_cvt_pk_bf16_f32 v244, v48, v49
	v_cvt_pk_bf16_f32 v245, v50, v51
	global_store_dwordx2 v252, v[242:243], s[16:17]
	global_store_dwordx2 v252, v[244:245], s[16:17] offset:2048
	s_waitcnt vmcnt(24)
	v_pk_mul_f32 v[238:239], v[40:41], v[218:219]
	v_pk_mul_f32 v[240:241], v[42:43], v[220:221]
	v_pk_mul_f32 v[242:243], v[44:45], v[218:219]
	v_pk_mul_f32 v[244:245], v[46:47], v[220:221]
	v_pk_fma_f32 v[44:45], v[44:45], v[214:215], v[238:239] neg_lo:[0,0,1] neg_hi:[0,0,1]
	v_pk_fma_f32 v[46:47], v[46:47], v[216:217], v[240:241] neg_lo:[0,0,1] neg_hi:[0,0,1]
	v_pk_fma_f32 v[40:41], v[40:41], v[214:215], v[242:243]
	v_pk_fma_f32 v[42:43], v[42:43], v[216:217], v[244:245]
	v_add_u32_e32 v251, 0x24000, v246
	v_cvt_pk_bf16_f32 v238, v44, v45
	v_cvt_pk_bf16_f32 v239, v46, v47
	v_cvt_pk_bf16_f32 v240, v40, v41
	v_cvt_pk_bf16_f32 v241, v42, v43
	global_store_dwordx2 v251, v[238:239], s[16:17]
	global_store_dwordx2 v251, v[240:241], s[16:17] offset:2048
	v_pk_mul_f32 v[238:239], v[32:33], v[218:219]
	v_pk_mul_f32 v[240:241], v[34:35], v[220:221]
	v_pk_mul_f32 v[242:243], v[36:37], v[218:219]
	v_pk_mul_f32 v[244:245], v[38:39], v[220:221]
	v_pk_fma_f32 v[36:37], v[36:37], v[214:215], v[238:239] neg_lo:[0,0,1] neg_hi:[0,0,1]
	v_pk_fma_f32 v[38:39], v[38:39], v[216:217], v[240:241] neg_lo:[0,0,1] neg_hi:[0,0,1]
	v_pk_fma_f32 v[32:33], v[32:33], v[214:215], v[242:243]
	v_pk_fma_f32 v[34:35], v[34:35], v[216:217], v[244:245]
	v_add_u32_e32 v252, 0x25000, v246
	v_cvt_pk_bf16_f32 v242, v36, v37
	v_cvt_pk_bf16_f32 v243, v38, v39
	v_cvt_pk_bf16_f32 v244, v32, v33
	v_cvt_pk_bf16_f32 v245, v34, v35
	global_store_dwordx2 v252, v[242:243], s[16:17]
	global_store_dwordx2 v252, v[244:245], s[16:17] offset:2048
	s_waitcnt vmcnt(18)
	v_pk_mul_f32 v[238:239], v[24:25], v[156:157]
	v_pk_mul_f32 v[240:241], v[26:27], v[158:159]
	v_pk_mul_f32 v[242:243], v[28:29], v[156:157]
	v_pk_mul_f32 v[244:245], v[30:31], v[158:159]
	v_pk_fma_f32 v[28:29], v[28:29], v[152:153], v[238:239] neg_lo:[0,0,1] neg_hi:[0,0,1]
	v_pk_fma_f32 v[30:31], v[30:31], v[154:155], v[240:241] neg_lo:[0,0,1] neg_hi:[0,0,1]
	v_pk_fma_f32 v[24:25], v[24:25], v[152:153], v[242:243]
	v_pk_fma_f32 v[26:27], v[26:27], v[154:155], v[244:245]
	v_add_u32_e32 v251, 0x28000, v246
	v_cvt_pk_bf16_f32 v238, v28, v29
	v_cvt_pk_bf16_f32 v239, v30, v31
	v_cvt_pk_bf16_f32 v240, v24, v25
	v_cvt_pk_bf16_f32 v241, v26, v27
	global_store_dwordx2 v251, v[238:239], s[16:17]
	global_store_dwordx2 v251, v[240:241], s[16:17] offset:2048
	v_pk_mul_f32 v[238:239], v[16:17], v[156:157]
	v_pk_mul_f32 v[240:241], v[18:19], v[158:159]
	v_pk_mul_f32 v[242:243], v[20:21], v[156:157]
	v_pk_mul_f32 v[244:245], v[22:23], v[158:159]
	v_pk_fma_f32 v[20:21], v[20:21], v[152:153], v[238:239] neg_lo:[0,0,1] neg_hi:[0,0,1]
	v_pk_fma_f32 v[22:23], v[22:23], v[154:155], v[240:241] neg_lo:[0,0,1] neg_hi:[0,0,1]
	v_pk_fma_f32 v[16:17], v[16:17], v[152:153], v[242:243]
	v_pk_fma_f32 v[18:19], v[18:19], v[154:155], v[244:245]
	v_add_u32_e32 v252, 0x29000, v246
	v_cvt_pk_bf16_f32 v242, v20, v21
	v_cvt_pk_bf16_f32 v243, v22, v23
	v_cvt_pk_bf16_f32 v244, v16, v17
	v_cvt_pk_bf16_f32 v245, v18, v19
	global_store_dwordx2 v252, v[242:243], s[16:17]
	global_store_dwordx2 v252, v[244:245], s[16:17] offset:2048
	s_waitcnt vmcnt(20)
	v_pk_mul_f32 v[238:239], v[8:9], v[164:165]
	v_pk_mul_f32 v[240:241], v[10:11], v[166:167]
	v_pk_mul_f32 v[242:243], v[12:13], v[164:165]
	v_pk_mul_f32 v[244:245], v[14:15], v[166:167]
	v_pk_fma_f32 v[12:13], v[12:13], v[160:161], v[238:239] neg_lo:[0,0,1] neg_hi:[0,0,1]
	v_pk_fma_f32 v[14:15], v[14:15], v[162:163], v[240:241] neg_lo:[0,0,1] neg_hi:[0,0,1]
	v_pk_fma_f32 v[8:9], v[8:9], v[160:161], v[242:243]
	v_pk_fma_f32 v[10:11], v[10:11], v[162:163], v[244:245]
	v_add_u32_e32 v251, 0x2c000, v246
	v_cvt_pk_bf16_f32 v238, v12, v13
	v_cvt_pk_bf16_f32 v239, v14, v15
	v_cvt_pk_bf16_f32 v240, v8, v9
	v_cvt_pk_bf16_f32 v241, v10, v11
	global_store_dwordx2 v251, v[238:239], s[16:17]
	global_store_dwordx2 v251, v[240:241], s[16:17] offset:2048
	v_pk_mul_f32 v[238:239], v[0:1], v[164:165]
	v_pk_mul_f32 v[240:241], v[2:3], v[166:167]
	v_pk_mul_f32 v[242:243], v[4:5], v[164:165]
	v_pk_mul_f32 v[244:245], v[6:7], v[166:167]
	v_pk_fma_f32 v[4:5], v[4:5], v[160:161], v[238:239] neg_lo:[0,0,1] neg_hi:[0,0,1]
	v_pk_fma_f32 v[6:7], v[6:7], v[162:163], v[240:241] neg_lo:[0,0,1] neg_hi:[0,0,1]
	v_pk_fma_f32 v[0:1], v[0:1], v[160:161], v[242:243]
	v_pk_fma_f32 v[2:3], v[2:3], v[162:163], v[244:245]
	v_add_u32_e32 v252, 0x2d000, v246
	v_cvt_pk_bf16_f32 v242, v4, v5
	v_cvt_pk_bf16_f32 v243, v6, v7
	v_cvt_pk_bf16_f32 v244, v0, v1
	v_cvt_pk_bf16_f32 v245, v2, v3
	global_store_dwordx2 v252, v[242:243], s[16:17]
	global_store_dwordx2 v252, v[244:245], s[16:17] offset:2048
	s_mov_b64 s[2:3], exec
	s_branch .LBB0_306
.Lepi_k:
	s_lshl_b32 s16, s2, 18
	s_and_b32 s17, s33, 1
	s_lshl_b32 s17, s17, 13
	s_add_i32 s16, s16, s17
	s_add_u32 s16, s66, s16
	s_addc_u32 s17, s67, 0
	s_add_u32 s16, s16, 0x1b801000
	s_addc_u32 s17, s17, 0
	s_and_b32 s18, s2, 7
	s_lshl_b32 s18, s18, 16
	s_add_u32 s18, s66, s18
	s_addc_u32 s19, s67, 0
	s_add_u32 s18, s18, 0x4500000
	s_addc_u32 s19, s19, 0
	s_add_u32 s20, s18, 0x80800
	s_addc_u32 s21, s19, 0
	s_lshr_b32 s24, s2, 3
	s_lshl_b32 s24, s24, 2
	s_and_b32 s25, s33, 1
	s_lshl_b32 s25, s25, 1
	s_add_i32 s24, s24, s25
	s_lshl_b32 s24, s24, 6
	s_and_b32 s25, s2, 7
	s_lshl_b32 s25, s25, 3
	s_add_i32 s24, s24, s25
	s_lshl_b32 s24, s24, 13
	s_add_u32 s24, s66, s24
	s_addc_u32 s25, s67, 0
	s_add_u32 s24, s24, 0xce01000
	s_addc_u32 s25, s25, 0
	s_and_b32 s26, s33, 1
	s_lshl_b32 s26, s26, 1
	v_and_b32_e32 v246, 15, v224
	v_lshrrev_b32_e32 v249, 8, v224
	v_lshl_or_b32 v247, v249, 6, v246
	v_sub_u32_e32 v212, 0x7f, v247
	v_lshlrev_b32_e32 v247, 8, v247
	v_bfe_u32 v250, v224, 4, 4
	v_lshl_or_b32 v247, v250, 4, v247
	v_lshlrev_b32_e32 v246, 4, v246
	v_lshl_or_b32 v246, v249, 16, v246
	v_lshlrev_b32_e32 v176, 14, v249
	v_lshl_or_b32 v176, v250, 8, v176
	v_bfe_u32 v249, v224, 4, 1
	v_lshl_or_b32 v246, v249, 3, v246
	v_bfe_u32 v249, v224, 7, 1
	v_lshl_or_b32 v246, v249, 10, v246
	v_bfe_u32 v249, v224, 5, 3
	v_and_b32_e32 v249, 3, v249
	v_lshl_or_b32 v246, v249, 8, v246
	v_bfe_u32 v249, v224, 2, 2
	v_lshl_or_b32 v176, v249, 4, v176
	v_and_b32_e32 v249, 3, v224
	v_lshl_or_b32 v176, v249, 1, v176
	v_mov_b32_e32 v248, v247
	global_load_dwordx4 v[152:155], v248, s[18:19]
	global_load_dwordx4 v[156:159], v248, s[20:21]
	v_add_u32_e32 v248, 0x1000, v247
	global_load_dwordx4 v[160:163], v248, s[18:19]
	global_load_dwordx4 v[164:167], v248, s[20:21]
	s_mov_b32 s27, s26
	v_cvt_f32_ubyte0_e32 v210, s27
	v_sub_f32_e32 v210, 0xc0a00000, v210
	v_exp_f32_e32 v210, v210
	s_nop 0
	v_sub_f32_e32 v210, 1.0, v210
	v_log_f32_e32 v210, v210
	s_nop 0
	s_add_i32 s27, s26, 1
	v_cvt_f32_ubyte0_e32 v211, s27
	v_sub_f32_e32 v211, 0xc0a00000, v211
	v_exp_f32_e32 v211, v211
	s_nop 0
	v_sub_f32_e32 v211, 1.0, v211
	v_log_f32_e32 v211, v211
	s_nop 0
	v_mov_b32_e32 v213, v212
	v_cvt_f32_u32_e32 v213, v213
	v_mul_f32_e32 v202, v210, v213
	v_exp_f32_e32 v202, v202
	v_mul_f32_e32 v203, v211, v213
	v_exp_f32_e32 v203, v203
	v_subrev_u32_e32 v213, 16, v212
	v_cvt_f32_u32_e32 v213, v213
	v_mul_f32_e32 v204, v210, v213
	v_exp_f32_e32 v204, v204
	v_mul_f32_e32 v205, v211, v213
	v_exp_f32_e32 v205, v205
	v_subrev_u32_e32 v213, 32, v212
	v_cvt_f32_u32_e32 v213, v213
	v_mul_f32_e32 v206, v210, v213
	v_exp_f32_e32 v206, v206
	v_mul_f32_e32 v207, v211, v213
	v_exp_f32_e32 v207, v207
	v_subrev_u32_e32 v213, 48, v212
	v_cvt_f32_u32_e32 v213, v213
	v_mul_f32_e32 v208, v210, v213
	v_exp_f32_e32 v208, v208
	v_mul_f32_e32 v209, v211, v213
	v_exp_f32_e32 v209, v209
	s_nop 0
	v_add_u32_e32 v248, 0x2000, v247
	global_load_dwordx4 v[168:171], v248, s[18:19]
	global_load_dwordx4 v[172:175], v248, s[20:21]
	s_waitcnt vmcnt(4)
	v_pk_mul_f32 v[238:239], v[120:121], v[156:157]
	v_pk_mul_f32 v[240:241], v[122:123], v[158:159]
	v_pk_mul_f32 v[242:243], v[124:125], v[156:157]
	v_pk_mul_f32 v[244:245], v[126:127], v[158:159]
	v_pk_fma_f32 v[124:125], v[124:125], v[152:153], v[238:239] neg_lo:[0,0,1] neg_hi:[0,0,1]
	v_pk_fma_f32 v[126:127], v[126:127], v[154:155], v[240:241] neg_lo:[0,0,1] neg_hi:[0,0,1]
	v_pk_fma_f32 v[120:121], v[120:121], v[152:153], v[242:243]
	v_pk_fma_f32 v[122:123], v[122:123], v[154:155], v[244:245]
	v_pk_mul_f32 v[124:125], v[124:125], s[14:15] op_sel_hi:[1,0]
	v_pk_mul_f32 v[126:127], v[126:127], s[14:15] op_sel_hi:[1,0]
	v_pk_mul_f32 v[120:121], v[120:121], s[14:15] op_sel_hi:[1,0]
	v_pk_mul_f32 v[122:123], v[122:123], s[14:15] op_sel_hi:[1,0]
	v_mov_b32_e32 v251, v246
	v_cvt_pk_bf16_f32 v238, v124, v125
	v_cvt_pk_bf16_f32 v239, v126, v127
	v_cvt_pk_bf16_f32 v240, v120, v121
	v_cvt_pk_bf16_f32 v241, v122, v123
	global_store_dwordx2 v251, v[238:239], s[16:17]
	global_store_dwordx2 v251, v[240:241], s[16:17] offset:2048
	v_mov_b32_e32 v177, v176
	v_add_u32_e32 v178, 0x1000, v176
	v_mul_f32_e32 v214, v202, v124
	v_bfe_u32 v253, v214, 16, 1
	v_add3_u32 v214, v214, v253, s76
	global_store_short_d16_hi v177, v214, s[24:25]
	v_mul_f32_e32 v215, v202, v120
	v_bfe_u32 v253, v215, 16, 1
	v_add3_u32 v215, v215, v253, s76
	global_store_short_d16_hi v178, v215, s[24:25]
	v_mul_f32_e32 v216, v202, v125
	v_bfe_u32 v253, v216, 16, 1
	v_add3_u32 v216, v216, v253, s76
	global_store_short_d16_hi v177, v216, s[24:25] offset:64
	v_mul_f32_e32 v217, v202, v121
	v_bfe_u32 v253, v217, 16, 1
	v_add3_u32 v217, v217, v253, s76
	global_store_short_d16_hi v178, v217, s[24:25] offset:64
	v_mul_f32_e32 v214, v202, v126
	v_bfe_u32 v253, v214, 16, 1
	v_add3_u32 v214, v214, v253, s76
	global_store_short_d16_hi v177, v214, s[24:25] offset:128
	v_mul_f32_e32 v215, v202, v122
	v_bfe_u32 v253, v215, 16, 1
	v_add3_u32 v215, v215, v253, s76
	global_store_short_d16_hi v178, v215, s[24:25] offset:128
	v_mul_f32_e32 v216, v202, v127
	v_bfe_u32 v253, v216, 16, 1
	v_add3_u32 v216, v216, v253, s76
	global_store_short_d16_hi v177, v216, s[24:25] offset:192
	v_mul_f32_e32 v217, v202, v123
	v_bfe_u32 v253, v217, 16, 1
	v_add3_u32 v217, v217, v253, s76
	global_store_short_d16_hi v178, v217, s[24:25] offset:192
	v_pk_mul_f32 v[238:239], v[112:113], v[156:157]
	v_pk_mul_f32 v[240:241], v[114:115], v[158:159]
	v_pk_mul_f32 v[242:243], v[116:117], v[156:157]
	v_pk_mul_f32 v[244:245], v[118:119], v[158:159]
	v_pk_fma_f32 v[116:117], v[116:117], v[152:153], v[238:239] neg_lo:[0,0,1] neg_hi:[0,0,1]
	v_pk_fma_f32 v[118:119], v[118:119], v[154:155], v[240:241] neg_lo:[0,0,1] neg_hi:[0,0,1]
	v_pk_fma_f32 v[112:113], v[112:113], v[152:153], v[242:243]
	v_pk_fma_f32 v[114:115], v[114:115], v[154:155], v[244:245]
	v_pk_mul_f32 v[116:117], v[116:117], s[14:15] op_sel_hi:[1,0]
	v_pk_mul_f32 v[118:119], v[118:119], s[14:15] op_sel_hi:[1,0]
	v_pk_mul_f32 v[112:113], v[112:113], s[14:15] op_sel_hi:[1,0]
	v_pk_mul_f32 v[114:115], v[114:115], s[14:15] op_sel_hi:[1,0]
	v_add_u32_e32 v252, 0x1000, v246
	v_cvt_pk_bf16_f32 v242, v116, v117
	v_cvt_pk_bf16_f32 v243, v118, v119
	v_cvt_pk_bf16_f32 v244, v112, v113
	v_cvt_pk_bf16_f32 v245, v114, v115
	global_store_dwordx2 v252, v[242:243], s[16:17]
	global_store_dwordx2 v252, v[244:245], s[16:17] offset:2048
	v_add_u32_e32 v179, 0x80000, v176
	v_add_u32_e32 v182, 0x81000, v176
	v_mul_f32_e32 v214, v203, v116
	v_bfe_u32 v253, v214, 16, 1
	v_add3_u32 v214, v214, v253, s76
	global_store_short_d16_hi v179, v214, s[24:25]
	v_mul_f32_e32 v215, v203, v112
	v_bfe_u32 v253, v215, 16, 1
	v_add3_u32 v215, v215, v253, s76
	global_store_short_d16_hi v182, v215, s[24:25]
	v_mul_f32_e32 v216, v203, v117
	v_bfe_u32 v253, v216, 16, 1
	v_add3_u32 v216, v216, v253, s76
	global_store_short_d16_hi v179, v216, s[24:25] offset:64
	v_mul_f32_e32 v217, v203, v113
	v_bfe_u32 v253, v217, 16, 1
	v_add3_u32 v217, v217, v253, s76
	global_store_short_d16_hi v182, v217, s[24:25] offset:64
	v_mul_f32_e32 v214, v203, v118
	v_bfe_u32 v253, v214, 16, 1
	v_add3_u32 v214, v214, v253, s76
	global_store_short_d16_hi v179, v214, s[24:25] offset:128
	v_mul_f32_e32 v215, v203, v114
	v_bfe_u32 v253, v215, 16, 1
	v_add3_u32 v215, v215, v253, s76
	global_store_short_d16_hi v182, v215, s[24:25] offset:128
	v_mul_f32_e32 v216, v203, v119
	v_bfe_u32 v253, v216, 16, 1
	v_add3_u32 v216, v216, v253, s76
	global_store_short_d16_hi v179, v216, s[24:25] offset:192
	v_mul_f32_e32 v217, v203, v115
	v_bfe_u32 v253, v217, 16, 1
	v_add3_u32 v217, v217, v253, s76
	global_store_short_d16_hi v182, v217, s[24:25] offset:192
	v_add_u32_e32 v248, 0x3000, v247
	global_load_dwordx4 v[152:155], v248, s[18:19]
	global_load_dwordx4 v[156:159], v248, s[20:21]
	s_waitcnt vmcnt(24)
	v_pk_mul_f32 v[238:239], v[104:105], v[164:165]
	v_pk_mul_f32 v[240:241], v[106:107], v[166:167]
	v_pk_mul_f32 v[242:243], v[108:109], v[164:165]
	v_pk_mul_f32 v[244:245], v[110:111], v[166:167]
	v_pk_fma_f32 v[108:109], v[108:109], v[160:161], v[238:239] neg_lo:[0,0,1] neg_hi:[0,0,1]
	v_pk_fma_f32 v[110:111], v[110:111], v[162:163], v[240:241] neg_lo:[0,0,1] neg_hi:[0,0,1]
	v_pk_fma_f32 v[104:105], v[104:105], v[160:161], v[242:243]
	v_pk_fma_f32 v[106:107], v[106:107], v[162:163], v[244:245]
	v_pk_mul_f32 v[108:109], v[108:109], s[14:15] op_sel_hi:[1,0]
	v_pk_mul_f32 v[110:111], v[110:111], s[14:15] op_sel_hi:[1,0]
	v_pk_mul_f32 v[104:105], v[104:105], s[14:15] op_sel_hi:[1,0]
	v_pk_mul_f32 v[106:107], v[106:107], s[14:15] op_sel_hi:[1,0]
	v_add_u32_e32 v251, 0x4000, v246
	v_cvt_pk_bf16_f32 v238, v108, v109
	v_cvt_pk_bf16_f32 v239, v110, v111
	v_cvt_pk_bf16_f32 v240, v104, v105
	v_cvt_pk_bf16_f32 v241, v106, v107
	global_store_dwordx2 v251, v[238:239], s[16:17]
	global_store_dwordx2 v251, v[240:241], s[16:17] offset:2048
	v_add_u32_e32 v177, 0x8, v176
	v_add_u32_e32 v178, 0x1008, v176
	v_mul_f32_e32 v214, v204, v108
	v_bfe_u32 v253, v214, 16, 1
	v_add3_u32 v214, v214, v253, s76
	global_store_short_d16_hi v177, v214, s[24:25]
	v_mul_f32_e32 v215, v204, v104
	v_bfe_u32 v253, v215, 16, 1
	v_add3_u32 v215, v215, v253, s76
	global_store_short_d16_hi v178, v215, s[24:25]
	v_mul_f32_e32 v216, v204, v109
	v_bfe_u32 v253, v216, 16, 1
	v_add3_u32 v216, v216, v253, s76
	global_store_short_d16_hi v177, v216, s[24:25] offset:64
	v_mul_f32_e32 v217, v204, v105
	v_bfe_u32 v253, v217, 16, 1
	v_add3_u32 v217, v217, v253, s76
	global_store_short_d16_hi v178, v217, s[24:25] offset:64
	v_mul_f32_e32 v214, v204, v110
	v_bfe_u32 v253, v214, 16, 1
	v_add3_u32 v214, v214, v253, s76
	global_store_short_d16_hi v177, v214, s[24:25] offset:128
	v_mul_f32_e32 v215, v204, v106
	v_bfe_u32 v253, v215, 16, 1
	v_add3_u32 v215, v215, v253, s76
	global_store_short_d16_hi v178, v215, s[24:25] offset:128
	v_mul_f32_e32 v216, v204, v111
	v_bfe_u32 v253, v216, 16, 1
	v_add3_u32 v216, v216, v253, s76
	global_store_short_d16_hi v177, v216, s[24:25] offset:192
	v_mul_f32_e32 v217, v204, v107
	v_bfe_u32 v253, v217, 16, 1
	v_add3_u32 v217, v217, v253, s76
	global_store_short_d16_hi v178, v217, s[24:25] offset:192
	v_pk_mul_f32 v[238:239], v[96:97], v[164:165]
	v_pk_mul_f32 v[240:241], v[98:99], v[166:167]
	v_pk_mul_f32 v[242:243], v[100:101], v[164:165]
	v_pk_mul_f32 v[244:245], v[102:103], v[166:167]
	v_pk_fma_f32 v[100:101], v[100:101], v[160:161], v[238:239] neg_lo:[0,0,1] neg_hi:[0,0,1]
	v_pk_fma_f32 v[102:103], v[102:103], v[162:163], v[240:241] neg_lo:[0,0,1] neg_hi:[0,0,1]
	v_pk_fma_f32 v[96:97], v[96:97], v[160:161], v[242:243]
	v_pk_fma_f32 v[98:99], v[98:99], v[162:163], v[244:245]
	v_pk_mul_f32 v[100:101], v[100:101], s[14:15] op_sel_hi:[1,0]
	v_pk_mul_f32 v[102:103], v[102:103], s[14:15] op_sel_hi:[1,0]
	v_pk_mul_f32 v[96:97], v[96:97], s[14:15] op_sel_hi:[1,0]
	v_pk_mul_f32 v[98:99], v[98:99], s[14:15] op_sel_hi:[1,0]
	v_add_u32_e32 v252, 0x5000, v246
	v_cvt_pk_bf16_f32 v242, v100, v101
	v_cvt_pk_bf16_f32 v243, v102, v103
	v_cvt_pk_bf16_f32 v244, v96, v97
	v_cvt_pk_bf16_f32 v245, v98, v99
	global_store_dwordx2 v252, v[242:243], s[16:17]
	global_store_dwordx2 v252, v[244:245], s[16:17] offset:2048
	v_add_u32_e32 v179, 0x80008, v176
	v_add_u32_e32 v182, 0x81008, v176
	v_mul_f32_e32 v214, v205, v100
	v_bfe_u32 v253, v214, 16, 1
	v_add3_u32 v214, v214, v253, s76
	global_store_short_d16_hi v179, v214, s[24:25]
	v_mul_f32_e32 v215, v205, v96
	v_bfe_u32 v253, v215, 16, 1
	v_add3_u32 v215, v215, v253, s76
	global_store_short_d16_hi v182, v215, s[24:25]
	v_mul_f32_e32 v216, v205, v101
	v_bfe_u32 v253, v216, 16, 1
	v_add3_u32 v216, v216, v253, s76
	global_store_short_d16_hi v179, v216, s[24:25] offset:64
	v_mul_f32_e32 v217, v205, v97
	v_bfe_u32 v253, v217, 16, 1
	v_add3_u32 v217, v217, v253, s76
	global_store_short_d16_hi v182, v217, s[24:25] offset:64
	v_mul_f32_e32 v214, v205, v102
	v_bfe_u32 v253, v214, 16, 1
	v_add3_u32 v214, v214, v253, s76
	global_store_short_d16_hi v179, v214, s[24:25] offset:128
	v_mul_f32_e32 v215, v205, v98
	v_bfe_u32 v253, v215, 16, 1
	v_add3_u32 v215, v215, v253, s76
	global_store_short_d16_hi v182, v215, s[24:25] offset:128
	v_mul_f32_e32 v216, v205, v103
	v_bfe_u32 v253, v216, 16, 1
	v_add3_u32 v216, v216, v253, s76
	global_store_short_d16_hi v179, v216, s[24:25] offset:192
	v_mul_f32_e32 v217, v205, v99
	v_bfe_u32 v253, v217, 16, 1
	v_add3_u32 v217, v217, v253, s76
	global_store_short_d16_hi v182, v217, s[24:25] offset:192
	v_add_u32_e32 v248, 0x8000, v247
	global_load_dwordx4 v[160:163], v248, s[18:19]
	global_load_dwordx4 v[164:167], v248, s[20:21]
	s_waitcnt vmcnt(44)
	v_pk_mul_f32 v[238:239], v[88:89], v[172:173]
	v_pk_mul_f32 v[240:241], v[90:91], v[174:175]
	v_pk_mul_f32 v[242:243], v[92:93], v[172:173]
	v_pk_mul_f32 v[244:245], v[94:95], v[174:175]
	v_pk_fma_f32 v[92:93], v[92:93], v[168:169], v[238:239] neg_lo:[0,0,1] neg_hi:[0,0,1]
	v_pk_fma_f32 v[94:95], v[94:95], v[170:171], v[240:241] neg_lo:[0,0,1] neg_hi:[0,0,1]
	v_pk_fma_f32 v[88:89], v[88:89], v[168:169], v[242:243]
	v_pk_fma_f32 v[90:91], v[90:91], v[170:171], v[244:245]
	v_pk_mul_f32 v[92:93], v[92:93], s[14:15] op_sel_hi:[1,0]
	v_pk_mul_f32 v[94:95], v[94:95], s[14:15] op_sel_hi:[1,0]
	v_pk_mul_f32 v[88:89], v[88:89], s[14:15] op_sel_hi:[1,0]
	v_pk_mul_f32 v[90:91], v[90:91], s[14:15] op_sel_hi:[1,0]
	v_add_u32_e32 v251, 0x8000, v246
	v_cvt_pk_bf16_f32 v238, v92, v93
	v_cvt_pk_bf16_f32 v239, v94, v95
	v_cvt_pk_bf16_f32 v240, v88, v89
	v_cvt_pk_bf16_f32 v241, v90, v91
	global_store_dwordx2 v251, v[238:239], s[16:17]
	global_store_dwordx2 v251, v[240:241], s[16:17] offset:2048
	v_add_u32_e32 v177, 0x2000, v176
	v_add_u32_e32 v178, 0x3000, v176
	v_mul_f32_e32 v214, v206, v92
	v_bfe_u32 v253, v214, 16, 1
	v_add3_u32 v214, v214, v253, s76
	global_store_short_d16_hi v177, v214, s[24:25]
	v_mul_f32_e32 v215, v206, v88
	v_bfe_u32 v253, v215, 16, 1
	v_add3_u32 v215, v215, v253, s76
	global_store_short_d16_hi v178, v215, s[24:25]
	v_mul_f32_e32 v216, v206, v93
	v_bfe_u32 v253, v216, 16, 1
	v_add3_u32 v216, v216, v253, s76
	global_store_short_d16_hi v177, v216, s[24:25] offset:64
	v_mul_f32_e32 v217, v206, v89
	v_bfe_u32 v253, v217, 16, 1
	v_add3_u32 v217, v217, v253, s76
	global_store_short_d16_hi v178, v217, s[24:25] offset:64
	v_mul_f32_e32 v214, v206, v94
	v_bfe_u32 v253, v214, 16, 1
	v_add3_u32 v214, v214, v253, s76
	global_store_short_d16_hi v177, v214, s[24:25] offset:128
	v_mul_f32_e32 v215, v206, v90
	v_bfe_u32 v253, v215, 16, 1
	v_add3_u32 v215, v215, v253, s76
	global_store_short_d16_hi v178, v215, s[24:25] offset:128
	v_mul_f32_e32 v216, v206, v95
	v_bfe_u32 v253, v216, 16, 1
	v_add3_u32 v216, v216, v253, s76
	global_store_short_d16_hi v177, v216, s[24:25] offset:192
	v_mul_f32_e32 v217, v206, v91
	v_bfe_u32 v253, v217, 16, 1
	v_add3_u32 v217, v217, v253, s76
	global_store_short_d16_hi v178, v217, s[24:25] offset:192
	v_pk_mul_f32 v[238:239], v[80:81], v[172:173]
	v_pk_mul_f32 v[240:241], v[82:83], v[174:175]
	v_pk_mul_f32 v[242:243], v[84:85], v[172:173]
	v_pk_mul_f32 v[244:245], v[86:87], v[174:175]
	v_pk_fma_f32 v[84:85], v[84:85], v[168:169], v[238:239] neg_lo:[0,0,1] neg_hi:[0,0,1]
	v_pk_fma_f32 v[86:87], v[86:87], v[170:171], v[240:241] neg_lo:[0,0,1] neg_hi:[0,0,1]
	v_pk_fma_f32 v[80:81], v[80:81], v[168:169], v[242:243]
	v_pk_fma_f32 v[82:83], v[82:83], v[170:171], v[244:245]
	v_pk_mul_f32 v[84:85], v[84:85], s[14:15] op_sel_hi:[1,0]
	v_pk_mul_f32 v[86:87], v[86:87], s[14:15] op_sel_hi:[1,0]
	v_pk_mul_f32 v[80:81], v[80:81], s[14:15] op_sel_hi:[1,0]
	v_pk_mul_f32 v[82:83], v[82:83], s[14:15] op_sel_hi:[1,0]
	v_add_u32_e32 v252, 0x9000, v246
	v_cvt_pk_bf16_f32 v242, v84, v85
	v_cvt_pk_bf16_f32 v243, v86, v87
	v_cvt_pk_bf16_f32 v244, v80, v81
	v_cvt_pk_bf16_f32 v245, v82, v83
	global_store_dwordx2 v252, v[242:243], s[16:17]
	global_store_dwordx2 v252, v[244:245], s[16:17] offset:2048
	v_add_u32_e32 v179, 0x82000, v176
	v_add_u32_e32 v182, 0x83000, v176
	v_mul_f32_e32 v214, v207, v84
	v_bfe_u32 v253, v214, 16, 1
	v_add3_u32 v214, v214, v253, s76
	global_store_short_d16_hi v179, v214, s[24:25]
	v_mul_f32_e32 v215, v207, v80
	v_bfe_u32 v253, v215, 16, 1
	v_add3_u32 v215, v215, v253, s76
	global_store_short_d16_hi v182, v215, s[24:25]
	v_mul_f32_e32 v216, v207, v85
	v_bfe_u32 v253, v216, 16, 1
	v_add3_u32 v216, v216, v253, s76
	global_store_short_d16_hi v179, v216, s[24:25] offset:64
	v_mul_f32_e32 v217, v207, v81
	v_bfe_u32 v253, v217, 16, 1
	v_add3_u32 v217, v217, v253, s76
	global_store_short_d16_hi v182, v217, s[24:25] offset:64
	v_mul_f32_e32 v214, v207, v86
	v_bfe_u32 v253, v214, 16, 1
	v_add3_u32 v214, v214, v253, s76
	global_store_short_d16_hi v179, v214, s[24:25] offset:128
	v_mul_f32_e32 v215, v207, v82
	v_bfe_u32 v253, v215, 16, 1
	v_add3_u32 v215, v215, v253, s76
	global_store_short_d16_hi v182, v215, s[24:25] offset:128
	v_mul_f32_e32 v216, v207, v87
	v_bfe_u32 v253, v216, 16, 1
	v_add3_u32 v216, v216, v253, s76
	global_store_short_d16_hi v179, v216, s[24:25] offset:192
	v_mul_f32_e32 v217, v207, v83
	v_bfe_u32 v253, v217, 16, 1
	v_add3_u32 v217, v217, v253, s76
	global_store_short_d16_hi v182, v217, s[24:25] offset:192
	v_add_u32_e32 v248, 0x9000, v247
	global_load_dwordx4 v[168:171], v248, s[18:19]
	global_load_dwordx4 v[172:175], v248, s[20:21]
	s_waitcnt vmcnt(44)
	v_pk_mul_f32 v[238:239], v[72:73], v[156:157]
	v_pk_mul_f32 v[240:241], v[74:75], v[158:159]
	v_pk_mul_f32 v[242:243], v[76:77], v[156:157]
	v_pk_mul_f32 v[244:245], v[78:79], v[158:159]
	v_pk_fma_f32 v[76:77], v[76:77], v[152:153], v[238:239] neg_lo:[0,0,1] neg_hi:[0,0,1]
	v_pk_fma_f32 v[78:79], v[78:79], v[154:155], v[240:241] neg_lo:[0,0,1] neg_hi:[0,0,1]
	v_pk_fma_f32 v[72:73], v[72:73], v[152:153], v[242:243]
	v_pk_fma_f32 v[74:75], v[74:75], v[154:155], v[244:245]
	v_pk_mul_f32 v[76:77], v[76:77], s[14:15] op_sel_hi:[1,0]
	v_pk_mul_f32 v[78:79], v[78:79], s[14:15] op_sel_hi:[1,0]
	v_pk_mul_f32 v[72:73], v[72:73], s[14:15] op_sel_hi:[1,0]
	v_pk_mul_f32 v[74:75], v[74:75], s[14:15] op_sel_hi:[1,0]
	v_add_u32_e32 v251, 0xc000, v246
	v_cvt_pk_bf16_f32 v238, v76, v77
	v_cvt_pk_bf16_f32 v239, v78, v79
	v_cvt_pk_bf16_f32 v240, v72, v73
	v_cvt_pk_bf16_f32 v241, v74, v75
	global_store_dwordx2 v251, v[238:239], s[16:17]
	global_store_dwordx2 v251, v[240:241], s[16:17] offset:2048
	v_add_u32_e32 v177, 0x2008, v176
	v_add_u32_e32 v178, 0x3008, v176
	v_mul_f32_e32 v214, v208, v76
	v_bfe_u32 v253, v214, 16, 1
	v_add3_u32 v214, v214, v253, s76
	global_store_short_d16_hi v177, v214, s[24:25]
	v_mul_f32_e32 v215, v208, v72
	v_bfe_u32 v253, v215, 16, 1
	v_add3_u32 v215, v215, v253, s76
	global_store_short_d16_hi v178, v215, s[24:25]
	v_mul_f32_e32 v216, v208, v77
	v_bfe_u32 v253, v216, 16, 1
	v_add3_u32 v216, v216, v253, s76
	global_store_short_d16_hi v177, v216, s[24:25] offset:64
	v_mul_f32_e32 v217, v208, v73
	v_bfe_u32 v253, v217, 16, 1
	v_add3_u32 v217, v217, v253, s76
	global_store_short_d16_hi v178, v217, s[24:25] offset:64
	v_mul_f32_e32 v214, v208, v78
	v_bfe_u32 v253, v214, 16, 1
	v_add3_u32 v214, v214, v253, s76
	global_store_short_d16_hi v177, v214, s[24:25] offset:128
	v_mul_f32_e32 v215, v208, v74
	v_bfe_u32 v253, v215, 16, 1
	v_add3_u32 v215, v215, v253, s76
	global_store_short_d16_hi v178, v215, s[24:25] offset:128
	v_mul_f32_e32 v216, v208, v79
	v_bfe_u32 v253, v216, 16, 1
	v_add3_u32 v216, v216, v253, s76
	global_store_short_d16_hi v177, v216, s[24:25] offset:192
	v_mul_f32_e32 v217, v208, v75
	v_bfe_u32 v253, v217, 16, 1
	v_add3_u32 v217, v217, v253, s76
	global_store_short_d16_hi v178, v217, s[24:25] offset:192
	v_pk_mul_f32 v[238:239], v[64:65], v[156:157]
	v_pk_mul_f32 v[240:241], v[66:67], v[158:159]
	v_pk_mul_f32 v[242:243], v[68:69], v[156:157]
	v_pk_mul_f32 v[244:245], v[70:71], v[158:159]
	v_pk_fma_f32 v[68:69], v[68:69], v[152:153], v[238:239] neg_lo:[0,0,1] neg_hi:[0,0,1]
	v_pk_fma_f32 v[70:71], v[70:71], v[154:155], v[240:241] neg_lo:[0,0,1] neg_hi:[0,0,1]
	v_pk_fma_f32 v[64:65], v[64:65], v[152:153], v[242:243]
	v_pk_fma_f32 v[66:67], v[66:67], v[154:155], v[244:245]
	v_pk_mul_f32 v[68:69], v[68:69], s[14:15] op_sel_hi:[1,0]
	v_pk_mul_f32 v[70:71], v[70:71], s[14:15] op_sel_hi:[1,0]
	v_pk_mul_f32 v[64:65], v[64:65], s[14:15] op_sel_hi:[1,0]
	v_pk_mul_f32 v[66:67], v[66:67], s[14:15] op_sel_hi:[1,0]
	v_add_u32_e32 v252, 0xd000, v246
	v_cvt_pk_bf16_f32 v242, v68, v69
	v_cvt_pk_bf16_f32 v243, v70, v71
	v_cvt_pk_bf16_f32 v244, v64, v65
	v_cvt_pk_bf16_f32 v245, v66, v67
	global_store_dwordx2 v252, v[242:243], s[16:17]
	global_store_dwordx2 v252, v[244:245], s[16:17] offset:2048
	v_add_u32_e32 v179, 0x82008, v176
	v_add_u32_e32 v182, 0x83008, v176
	v_mul_f32_e32 v214, v209, v68
	v_bfe_u32 v253, v214, 16, 1
	v_add3_u32 v214, v214, v253, s76
	global_store_short_d16_hi v179, v214, s[24:25]
	v_mul_f32_e32 v215, v209, v64
	v_bfe_u32 v253, v215, 16, 1
	v_add3_u32 v215, v215, v253, s76
	global_store_short_d16_hi v182, v215, s[24:25]
	v_mul_f32_e32 v216, v209, v69
	v_bfe_u32 v253, v216, 16, 1
	v_add3_u32 v216, v216, v253, s76
	global_store_short_d16_hi v179, v216, s[24:25] offset:64
	v_mul_f32_e32 v217, v209, v65
	v_bfe_u32 v253, v217, 16, 1
	v_add3_u32 v217, v217, v253, s76
	global_store_short_d16_hi v182, v217, s[24:25] offset:64
	v_mul_f32_e32 v214, v209, v70
	v_bfe_u32 v253, v214, 16, 1
	v_add3_u32 v214, v214, v253, s76
	global_store_short_d16_hi v179, v214, s[24:25] offset:128
	v_mul_f32_e32 v215, v209, v66
	v_bfe_u32 v253, v215, 16, 1
	v_add3_u32 v215, v215, v253, s76
	global_store_short_d16_hi v182, v215, s[24:25] offset:128
	v_mul_f32_e32 v216, v209, v71
	v_bfe_u32 v253, v216, 16, 1
	v_add3_u32 v216, v216, v253, s76
	global_store_short_d16_hi v179, v216, s[24:25] offset:192
	v_mul_f32_e32 v217, v209, v67
	v_bfe_u32 v253, v217, 16, 1
	v_add3_u32 v217, v217, v253, s76
	global_store_short_d16_hi v182, v217, s[24:25] offset:192
	v_add_u32_e32 v248, 0xa000, v247
	global_load_dwordx4 v[152:155], v248, s[18:19]
	global_load_dwordx4 v[156:159], v248, s[20:21]
	s_waitcnt vmcnt(44)
	v_pk_mul_f32 v[238:239], v[56:57], v[164:165]
	v_pk_mul_f32 v[240:241], v[58:59], v[166:167]
	v_pk_mul_f32 v[242:243], v[60:61], v[164:165]
	v_pk_mul_f32 v[244:245], v[62:63], v[166:167]
	v_pk_fma_f32 v[60:61], v[60:61], v[160:161], v[238:239] neg_lo:[0,0,1] neg_hi:[0,0,1]
	v_pk_fma_f32 v[62:63], v[62:63], v[162:163], v[240:241] neg_lo:[0,0,1] neg_hi:[0,0,1]
	v_pk_fma_f32 v[56:57], v[56:57], v[160:161], v[242:243]
	v_pk_fma_f32 v[58:59], v[58:59], v[162:163], v[244:245]
	v_pk_mul_f32 v[60:61], v[60:61], s[14:15] op_sel_hi:[1,0]
	v_pk_mul_f32 v[62:63], v[62:63], s[14:15] op_sel_hi:[1,0]
	v_pk_mul_f32 v[56:57], v[56:57], s[14:15] op_sel_hi:[1,0]
	v_pk_mul_f32 v[58:59], v[58:59], s[14:15] op_sel_hi:[1,0]
	v_add_u32_e32 v251, 0x20000, v246
	v_cvt_pk_bf16_f32 v238, v60, v61
	v_cvt_pk_bf16_f32 v239, v62, v63
	v_cvt_pk_bf16_f32 v240, v56, v57
	v_cvt_pk_bf16_f32 v241, v58, v59
	global_store_dwordx2 v251, v[238:239], s[16:17]
	global_store_dwordx2 v251, v[240:241], s[16:17] offset:2048
	v_add_u32_e32 v177, 0x8000, v176
	v_add_u32_e32 v178, 0x9000, v176
	v_mul_f32_e32 v214, v202, v60
	v_bfe_u32 v253, v214, 16, 1
	v_add3_u32 v214, v214, v253, s76
	global_store_short_d16_hi v177, v214, s[24:25]
	v_mul_f32_e32 v215, v202, v56
	v_bfe_u32 v253, v215, 16, 1
	v_add3_u32 v215, v215, v253, s76
	global_store_short_d16_hi v178, v215, s[24:25]
	v_mul_f32_e32 v216, v202, v61
	v_bfe_u32 v253, v216, 16, 1
	v_add3_u32 v216, v216, v253, s76
	global_store_short_d16_hi v177, v216, s[24:25] offset:64
	v_mul_f32_e32 v217, v202, v57
	v_bfe_u32 v253, v217, 16, 1
	v_add3_u32 v217, v217, v253, s76
	global_store_short_d16_hi v178, v217, s[24:25] offset:64
	v_mul_f32_e32 v214, v202, v62
	v_bfe_u32 v253, v214, 16, 1
	v_add3_u32 v214, v214, v253, s76
	global_store_short_d16_hi v177, v214, s[24:25] offset:128
	v_mul_f32_e32 v215, v202, v58
	v_bfe_u32 v253, v215, 16, 1
	v_add3_u32 v215, v215, v253, s76
	global_store_short_d16_hi v178, v215, s[24:25] offset:128
	v_mul_f32_e32 v216, v202, v63
	v_bfe_u32 v253, v216, 16, 1
	v_add3_u32 v216, v216, v253, s76
	global_store_short_d16_hi v177, v216, s[24:25] offset:192
	v_mul_f32_e32 v217, v202, v59
	v_bfe_u32 v253, v217, 16, 1
	v_add3_u32 v217, v217, v253, s76
	global_store_short_d16_hi v178, v217, s[24:25] offset:192
	v_pk_mul_f32 v[238:239], v[48:49], v[164:165]
	v_pk_mul_f32 v[240:241], v[50:51], v[166:167]
	v_pk_mul_f32 v[242:243], v[52:53], v[164:165]
	v_pk_mul_f32 v[244:245], v[54:55], v[166:167]
	v_pk_fma_f32 v[52:53], v[52:53], v[160:161], v[238:239] neg_lo:[0,0,1] neg_hi:[0,0,1]
	v_pk_fma_f32 v[54:55], v[54:55], v[162:163], v[240:241] neg_lo:[0,0,1] neg_hi:[0,0,1]
	v_pk_fma_f32 v[48:49], v[48:49], v[160:161], v[242:243]
	v_pk_fma_f32 v[50:51], v[50:51], v[162:163], v[244:245]
	v_pk_mul_f32 v[52:53], v[52:53], s[14:15] op_sel_hi:[1,0]
	v_pk_mul_f32 v[54:55], v[54:55], s[14:15] op_sel_hi:[1,0]
	v_pk_mul_f32 v[48:49], v[48:49], s[14:15] op_sel_hi:[1,0]
	v_pk_mul_f32 v[50:51], v[50:51], s[14:15] op_sel_hi:[1,0]
	v_add_u32_e32 v252, 0x21000, v246
	v_cvt_pk_bf16_f32 v242, v52, v53
	v_cvt_pk_bf16_f32 v243, v54, v55
	v_cvt_pk_bf16_f32 v244, v48, v49
	v_cvt_pk_bf16_f32 v245, v50, v51
	global_store_dwordx2 v252, v[242:243], s[16:17]
	global_store_dwordx2 v252, v[244:245], s[16:17] offset:2048
	v_add_u32_e32 v179, 0x88000, v176
	v_add_u32_e32 v182, 0x89000, v176
	v_mul_f32_e32 v214, v203, v52
	v_bfe_u32 v253, v214, 16, 1
	v_add3_u32 v214, v214, v253, s76
	global_store_short_d16_hi v179, v214, s[24:25]
	v_mul_f32_e32 v215, v203, v48
	v_bfe_u32 v253, v215, 16, 1
	v_add3_u32 v215, v215, v253, s76
	global_store_short_d16_hi v182, v215, s[24:25]
	v_mul_f32_e32 v216, v203, v53
	v_bfe_u32 v253, v216, 16, 1
	v_add3_u32 v216, v216, v253, s76
	global_store_short_d16_hi v179, v216, s[24:25] offset:64
	v_mul_f32_e32 v217, v203, v49
	v_bfe_u32 v253, v217, 16, 1
	v_add3_u32 v217, v217, v253, s76
	global_store_short_d16_hi v182, v217, s[24:25] offset:64
	v_mul_f32_e32 v214, v203, v54
	v_bfe_u32 v253, v214, 16, 1
	v_add3_u32 v214, v214, v253, s76
	global_store_short_d16_hi v179, v214, s[24:25] offset:128
	v_mul_f32_e32 v215, v203, v50
	v_bfe_u32 v253, v215, 16, 1
	v_add3_u32 v215, v215, v253, s76
	global_store_short_d16_hi v182, v215, s[24:25] offset:128
	v_mul_f32_e32 v216, v203, v55
	v_bfe_u32 v253, v216, 16, 1
	v_add3_u32 v216, v216, v253, s76
	global_store_short_d16_hi v179, v216, s[24:25] offset:192
	v_mul_f32_e32 v217, v203, v51
	v_bfe_u32 v253, v217, 16, 1
	v_add3_u32 v217, v217, v253, s76
	global_store_short_d16_hi v182, v217, s[24:25] offset:192
	v_add_u32_e32 v248, 0xb000, v247
	global_load_dwordx4 v[160:163], v248, s[18:19]
	global_load_dwordx4 v[164:167], v248, s[20:21]
	s_waitcnt vmcnt(44)
	v_pk_mul_f32 v[238:239], v[40:41], v[172:173]
	v_pk_mul_f32 v[240:241], v[42:43], v[174:175]
	v_pk_mul_f32 v[242:243], v[44:45], v[172:173]
	v_pk_mul_f32 v[244:245], v[46:47], v[174:175]
	v_pk_fma_f32 v[44:45], v[44:45], v[168:169], v[238:239] neg_lo:[0,0,1] neg_hi:[0,0,1]
	v_pk_fma_f32 v[46:47], v[46:47], v[170:171], v[240:241] neg_lo:[0,0,1] neg_hi:[0,0,1]
	v_pk_fma_f32 v[40:41], v[40:41], v[168:169], v[242:243]
	v_pk_fma_f32 v[42:43], v[42:43], v[170:171], v[244:245]
	v_pk_mul_f32 v[44:45], v[44:45], s[14:15] op_sel_hi:[1,0]
	v_pk_mul_f32 v[46:47], v[46:47], s[14:15] op_sel_hi:[1,0]
	v_pk_mul_f32 v[40:41], v[40:41], s[14:15] op_sel_hi:[1,0]
	v_pk_mul_f32 v[42:43], v[42:43], s[14:15] op_sel_hi:[1,0]
	v_add_u32_e32 v251, 0x24000, v246
	v_cvt_pk_bf16_f32 v238, v44, v45
	v_cvt_pk_bf16_f32 v239, v46, v47
	v_cvt_pk_bf16_f32 v240, v40, v41
	v_cvt_pk_bf16_f32 v241, v42, v43
	global_store_dwordx2 v251, v[238:239], s[16:17]
	global_store_dwordx2 v251, v[240:241], s[16:17] offset:2048
	v_add_u32_e32 v177, 0x8008, v176
	v_add_u32_e32 v178, 0x9008, v176
	v_mul_f32_e32 v214, v204, v44
	v_bfe_u32 v253, v214, 16, 1
	v_add3_u32 v214, v214, v253, s76
	global_store_short_d16_hi v177, v214, s[24:25]
	v_mul_f32_e32 v215, v204, v40
	v_bfe_u32 v253, v215, 16, 1
	v_add3_u32 v215, v215, v253, s76
	global_store_short_d16_hi v178, v215, s[24:25]
	v_mul_f32_e32 v216, v204, v45
	v_bfe_u32 v253, v216, 16, 1
	v_add3_u32 v216, v216, v253, s76
	global_store_short_d16_hi v177, v216, s[24:25] offset:64
	v_mul_f32_e32 v217, v204, v41
	v_bfe_u32 v253, v217, 16, 1
	v_add3_u32 v217, v217, v253, s76
	global_store_short_d16_hi v178, v217, s[24:25] offset:64
	v_mul_f32_e32 v214, v204, v46
	v_bfe_u32 v253, v214, 16, 1
	v_add3_u32 v214, v214, v253, s76
	global_store_short_d16_hi v177, v214, s[24:25] offset:128
	v_mul_f32_e32 v215, v204, v42
	v_bfe_u32 v253, v215, 16, 1
	v_add3_u32 v215, v215, v253, s76
	global_store_short_d16_hi v178, v215, s[24:25] offset:128
	v_mul_f32_e32 v216, v204, v47
	v_bfe_u32 v253, v216, 16, 1
	v_add3_u32 v216, v216, v253, s76
	global_store_short_d16_hi v177, v216, s[24:25] offset:192
	v_mul_f32_e32 v217, v204, v43
	v_bfe_u32 v253, v217, 16, 1
	v_add3_u32 v217, v217, v253, s76
	global_store_short_d16_hi v178, v217, s[24:25] offset:192
	v_pk_mul_f32 v[238:239], v[32:33], v[172:173]
	v_pk_mul_f32 v[240:241], v[34:35], v[174:175]
	v_pk_mul_f32 v[242:243], v[36:37], v[172:173]
	v_pk_mul_f32 v[244:245], v[38:39], v[174:175]
	v_pk_fma_f32 v[36:37], v[36:37], v[168:169], v[238:239] neg_lo:[0,0,1] neg_hi:[0,0,1]
	v_pk_fma_f32 v[38:39], v[38:39], v[170:171], v[240:241] neg_lo:[0,0,1] neg_hi:[0,0,1]
	v_pk_fma_f32 v[32:33], v[32:33], v[168:169], v[242:243]
	v_pk_fma_f32 v[34:35], v[34:35], v[170:171], v[244:245]
	v_pk_mul_f32 v[36:37], v[36:37], s[14:15] op_sel_hi:[1,0]
	v_pk_mul_f32 v[38:39], v[38:39], s[14:15] op_sel_hi:[1,0]
	v_pk_mul_f32 v[32:33], v[32:33], s[14:15] op_sel_hi:[1,0]
	v_pk_mul_f32 v[34:35], v[34:35], s[14:15] op_sel_hi:[1,0]
	v_add_u32_e32 v252, 0x25000, v246
	v_cvt_pk_bf16_f32 v242, v36, v37
	v_cvt_pk_bf16_f32 v243, v38, v39
	v_cvt_pk_bf16_f32 v244, v32, v33
	v_cvt_pk_bf16_f32 v245, v34, v35
	global_store_dwordx2 v252, v[242:243], s[16:17]
	global_store_dwordx2 v252, v[244:245], s[16:17] offset:2048
	v_add_u32_e32 v179, 0x88008, v176
	v_add_u32_e32 v182, 0x89008, v176
	v_mul_f32_e32 v214, v205, v36
	v_bfe_u32 v253, v214, 16, 1
	v_add3_u32 v214, v214, v253, s76
	global_store_short_d16_hi v179, v214, s[24:25]
	v_mul_f32_e32 v215, v205, v32
	v_bfe_u32 v253, v215, 16, 1
	v_add3_u32 v215, v215, v253, s76
	global_store_short_d16_hi v182, v215, s[24:25]
	v_mul_f32_e32 v216, v205, v37
	v_bfe_u32 v253, v216, 16, 1
	v_add3_u32 v216, v216, v253, s76
	global_store_short_d16_hi v179, v216, s[24:25] offset:64
	v_mul_f32_e32 v217, v205, v33
	v_bfe_u32 v253, v217, 16, 1
	v_add3_u32 v217, v217, v253, s76
	global_store_short_d16_hi v182, v217, s[24:25] offset:64
	v_mul_f32_e32 v214, v205, v38
	v_bfe_u32 v253, v214, 16, 1
	v_add3_u32 v214, v214, v253, s76
	global_store_short_d16_hi v179, v214, s[24:25] offset:128
	v_mul_f32_e32 v215, v205, v34
	v_bfe_u32 v253, v215, 16, 1
	v_add3_u32 v215, v215, v253, s76
	global_store_short_d16_hi v182, v215, s[24:25] offset:128
	v_mul_f32_e32 v216, v205, v39
	v_bfe_u32 v253, v216, 16, 1
	v_add3_u32 v216, v216, v253, s76
	global_store_short_d16_hi v179, v216, s[24:25] offset:192
	v_mul_f32_e32 v217, v205, v35
	v_bfe_u32 v253, v217, 16, 1
	v_add3_u32 v217, v217, v253, s76
	global_store_short_d16_hi v182, v217, s[24:25] offset:192
	s_waitcnt vmcnt(42)
	v_pk_mul_f32 v[238:239], v[24:25], v[156:157]
	v_pk_mul_f32 v[240:241], v[26:27], v[158:159]
	v_pk_mul_f32 v[242:243], v[28:29], v[156:157]
	v_pk_mul_f32 v[244:245], v[30:31], v[158:159]
	v_pk_fma_f32 v[28:29], v[28:29], v[152:153], v[238:239] neg_lo:[0,0,1] neg_hi:[0,0,1]
	v_pk_fma_f32 v[30:31], v[30:31], v[154:155], v[240:241] neg_lo:[0,0,1] neg_hi:[0,0,1]
	v_pk_fma_f32 v[24:25], v[24:25], v[152:153], v[242:243]
	v_pk_fma_f32 v[26:27], v[26:27], v[154:155], v[244:245]
	v_pk_mul_f32 v[28:29], v[28:29], s[14:15] op_sel_hi:[1,0]
	v_pk_mul_f32 v[30:31], v[30:31], s[14:15] op_sel_hi:[1,0]
	v_pk_mul_f32 v[24:25], v[24:25], s[14:15] op_sel_hi:[1,0]
	v_pk_mul_f32 v[26:27], v[26:27], s[14:15] op_sel_hi:[1,0]
	v_add_u32_e32 v251, 0x28000, v246
	v_cvt_pk_bf16_f32 v238, v28, v29
	v_cvt_pk_bf16_f32 v239, v30, v31
	v_cvt_pk_bf16_f32 v240, v24, v25
	v_cvt_pk_bf16_f32 v241, v26, v27
	global_store_dwordx2 v251, v[238:239], s[16:17]
	global_store_dwordx2 v251, v[240:241], s[16:17] offset:2048
	v_add_u32_e32 v177, 0xa000, v176
	v_add_u32_e32 v178, 0xb000, v176
	v_mul_f32_e32 v214, v206, v28
	v_bfe_u32 v253, v214, 16, 1
	v_add3_u32 v214, v214, v253, s76
	global_store_short_d16_hi v177, v214, s[24:25]
	v_mul_f32_e32 v215, v206, v24
	v_bfe_u32 v253, v215, 16, 1
	v_add3_u32 v215, v215, v253, s76
	global_store_short_d16_hi v178, v215, s[24:25]
	v_mul_f32_e32 v216, v206, v29
	v_bfe_u32 v253, v216, 16, 1
	v_add3_u32 v216, v216, v253, s76
	global_store_short_d16_hi v177, v216, s[24:25] offset:64
	v_mul_f32_e32 v217, v206, v25
	v_bfe_u32 v253, v217, 16, 1
	v_add3_u32 v217, v217, v253, s76
	global_store_short_d16_hi v178, v217, s[24:25] offset:64
	v_mul_f32_e32 v214, v206, v30
	v_bfe_u32 v253, v214, 16, 1
	v_add3_u32 v214, v214, v253, s76
	global_store_short_d16_hi v177, v214, s[24:25] offset:128
	v_mul_f32_e32 v215, v206, v26
	v_bfe_u32 v253, v215, 16, 1
	v_add3_u32 v215, v215, v253, s76
	global_store_short_d16_hi v178, v215, s[24:25] offset:128
	v_mul_f32_e32 v216, v206, v31
	v_bfe_u32 v253, v216, 16, 1
	v_add3_u32 v216, v216, v253, s76
	global_store_short_d16_hi v177, v216, s[24:25] offset:192
	v_mul_f32_e32 v217, v206, v27
	v_bfe_u32 v253, v217, 16, 1
	v_add3_u32 v217, v217, v253, s76
	global_store_short_d16_hi v178, v217, s[24:25] offset:192
	v_pk_mul_f32 v[238:239], v[16:17], v[156:157]
	v_pk_mul_f32 v[240:241], v[18:19], v[158:159]
	v_pk_mul_f32 v[242:243], v[20:21], v[156:157]
	v_pk_mul_f32 v[244:245], v[22:23], v[158:159]
	v_pk_fma_f32 v[20:21], v[20:21], v[152:153], v[238:239] neg_lo:[0,0,1] neg_hi:[0,0,1]
	v_pk_fma_f32 v[22:23], v[22:23], v[154:155], v[240:241] neg_lo:[0,0,1] neg_hi:[0,0,1]
	v_pk_fma_f32 v[16:17], v[16:17], v[152:153], v[242:243]
	v_pk_fma_f32 v[18:19], v[18:19], v[154:155], v[244:245]
	v_pk_mul_f32 v[20:21], v[20:21], s[14:15] op_sel_hi:[1,0]
	v_pk_mul_f32 v[22:23], v[22:23], s[14:15] op_sel_hi:[1,0]
	v_pk_mul_f32 v[16:17], v[16:17], s[14:15] op_sel_hi:[1,0]
	v_pk_mul_f32 v[18:19], v[18:19], s[14:15] op_sel_hi:[1,0]
	v_add_u32_e32 v252, 0x29000, v246
	v_cvt_pk_bf16_f32 v242, v20, v21
	v_cvt_pk_bf16_f32 v243, v22, v23
	v_cvt_pk_bf16_f32 v244, v16, v17
	v_cvt_pk_bf16_f32 v245, v18, v19
	global_store_dwordx2 v252, v[242:243], s[16:17]
	global_store_dwordx2 v252, v[244:245], s[16:17] offset:2048
	v_add_u32_e32 v179, 0x8a000, v176
	v_add_u32_e32 v182, 0x8b000, v176
	v_mul_f32_e32 v214, v207, v20
	v_bfe_u32 v253, v214, 16, 1
	v_add3_u32 v214, v214, v253, s76
	global_store_short_d16_hi v179, v214, s[24:25]
	v_mul_f32_e32 v215, v207, v16
	v_bfe_u32 v253, v215, 16, 1
	v_add3_u32 v215, v215, v253, s76
	global_store_short_d16_hi v182, v215, s[24:25]
	v_mul_f32_e32 v216, v207, v21
	v_bfe_u32 v253, v216, 16, 1
	v_add3_u32 v216, v216, v253, s76
	global_store_short_d16_hi v179, v216, s[24:25] offset:64
	v_mul_f32_e32 v217, v207, v17
	v_bfe_u32 v253, v217, 16, 1
	v_add3_u32 v217, v217, v253, s76
	global_store_short_d16_hi v182, v217, s[24:25] offset:64
	v_mul_f32_e32 v214, v207, v22
	v_bfe_u32 v253, v214, 16, 1
	v_add3_u32 v214, v214, v253, s76
	global_store_short_d16_hi v179, v214, s[24:25] offset:128
	v_mul_f32_e32 v215, v207, v18
	v_bfe_u32 v253, v215, 16, 1
	v_add3_u32 v215, v215, v253, s76
	global_store_short_d16_hi v182, v215, s[24:25] offset:128
	v_mul_f32_e32 v216, v207, v23
	v_bfe_u32 v253, v216, 16, 1
	v_add3_u32 v216, v216, v253, s76
	global_store_short_d16_hi v179, v216, s[24:25] offset:192
	v_mul_f32_e32 v217, v207, v19
	v_bfe_u32 v253, v217, 16, 1
	v_add3_u32 v217, v217, v253, s76
	global_store_short_d16_hi v182, v217, s[24:25] offset:192
	s_waitcnt vmcnt(40)
	v_pk_mul_f32 v[238:239], v[8:9], v[164:165]
	v_pk_mul_f32 v[240:241], v[10:11], v[166:167]
	v_pk_mul_f32 v[242:243], v[12:13], v[164:165]
	v_pk_mul_f32 v[244:245], v[14:15], v[166:167]
	v_pk_fma_f32 v[12:13], v[12:13], v[160:161], v[238:239] neg_lo:[0,0,1] neg_hi:[0,0,1]
	v_pk_fma_f32 v[14:15], v[14:15], v[162:163], v[240:241] neg_lo:[0,0,1] neg_hi:[0,0,1]
	v_pk_fma_f32 v[8:9], v[8:9], v[160:161], v[242:243]
	v_pk_fma_f32 v[10:11], v[10:11], v[162:163], v[244:245]
	v_pk_mul_f32 v[12:13], v[12:13], s[14:15] op_sel_hi:[1,0]
	v_pk_mul_f32 v[14:15], v[14:15], s[14:15] op_sel_hi:[1,0]
	v_pk_mul_f32 v[8:9], v[8:9], s[14:15] op_sel_hi:[1,0]
	v_pk_mul_f32 v[10:11], v[10:11], s[14:15] op_sel_hi:[1,0]
	v_add_u32_e32 v251, 0x2c000, v246
	v_cvt_pk_bf16_f32 v238, v12, v13
	v_cvt_pk_bf16_f32 v239, v14, v15
	v_cvt_pk_bf16_f32 v240, v8, v9
	v_cvt_pk_bf16_f32 v241, v10, v11
	global_store_dwordx2 v251, v[238:239], s[16:17]
	global_store_dwordx2 v251, v[240:241], s[16:17] offset:2048
	v_add_u32_e32 v177, 0xa008, v176
	v_add_u32_e32 v178, 0xb008, v176
	v_mul_f32_e32 v214, v208, v12
	v_bfe_u32 v253, v214, 16, 1
	v_add3_u32 v214, v214, v253, s76
	global_store_short_d16_hi v177, v214, s[24:25]
	v_mul_f32_e32 v215, v208, v8
	v_bfe_u32 v253, v215, 16, 1
	v_add3_u32 v215, v215, v253, s76
	global_store_short_d16_hi v178, v215, s[24:25]
	v_mul_f32_e32 v216, v208, v13
	v_bfe_u32 v253, v216, 16, 1
	v_add3_u32 v216, v216, v253, s76
	global_store_short_d16_hi v177, v216, s[24:25] offset:64
	v_mul_f32_e32 v217, v208, v9
	v_bfe_u32 v253, v217, 16, 1
	v_add3_u32 v217, v217, v253, s76
	global_store_short_d16_hi v178, v217, s[24:25] offset:64
	v_mul_f32_e32 v214, v208, v14
	v_bfe_u32 v253, v214, 16, 1
	v_add3_u32 v214, v214, v253, s76
	global_store_short_d16_hi v177, v214, s[24:25] offset:128
	v_mul_f32_e32 v215, v208, v10
	v_bfe_u32 v253, v215, 16, 1
	v_add3_u32 v215, v215, v253, s76
	global_store_short_d16_hi v178, v215, s[24:25] offset:128
	v_mul_f32_e32 v216, v208, v15
	v_bfe_u32 v253, v216, 16, 1
	v_add3_u32 v216, v216, v253, s76
	global_store_short_d16_hi v177, v216, s[24:25] offset:192
	v_mul_f32_e32 v217, v208, v11
	v_bfe_u32 v253, v217, 16, 1
	v_add3_u32 v217, v217, v253, s76
	global_store_short_d16_hi v178, v217, s[24:25] offset:192
	v_pk_mul_f32 v[238:239], v[0:1], v[164:165]
	v_pk_mul_f32 v[240:241], v[2:3], v[166:167]
	v_pk_mul_f32 v[242:243], v[4:5], v[164:165]
	v_pk_mul_f32 v[244:245], v[6:7], v[166:167]
	v_pk_fma_f32 v[4:5], v[4:5], v[160:161], v[238:239] neg_lo:[0,0,1] neg_hi:[0,0,1]
	v_pk_fma_f32 v[6:7], v[6:7], v[162:163], v[240:241] neg_lo:[0,0,1] neg_hi:[0,0,1]
	v_pk_fma_f32 v[0:1], v[0:1], v[160:161], v[242:243]
	v_pk_fma_f32 v[2:3], v[2:3], v[162:163], v[244:245]
	v_pk_mul_f32 v[4:5], v[4:5], s[14:15] op_sel_hi:[1,0]
	v_pk_mul_f32 v[6:7], v[6:7], s[14:15] op_sel_hi:[1,0]
	v_pk_mul_f32 v[0:1], v[0:1], s[14:15] op_sel_hi:[1,0]
	v_pk_mul_f32 v[2:3], v[2:3], s[14:15] op_sel_hi:[1,0]
	v_add_u32_e32 v252, 0x2d000, v246
	v_cvt_pk_bf16_f32 v242, v4, v5
	v_cvt_pk_bf16_f32 v243, v6, v7
	v_cvt_pk_bf16_f32 v244, v0, v1
	v_cvt_pk_bf16_f32 v245, v2, v3
	global_store_dwordx2 v252, v[242:243], s[16:17]
	global_store_dwordx2 v252, v[244:245], s[16:17] offset:2048
	v_add_u32_e32 v179, 0x8a008, v176
	v_add_u32_e32 v182, 0x8b008, v176
	v_mul_f32_e32 v214, v209, v4
	v_bfe_u32 v253, v214, 16, 1
	v_add3_u32 v214, v214, v253, s76
	global_store_short_d16_hi v179, v214, s[24:25]
	v_mul_f32_e32 v215, v209, v0
	v_bfe_u32 v253, v215, 16, 1
	v_add3_u32 v215, v215, v253, s76
	global_store_short_d16_hi v182, v215, s[24:25]
	v_mul_f32_e32 v216, v209, v5
	v_bfe_u32 v253, v216, 16, 1
	v_add3_u32 v216, v216, v253, s76
	global_store_short_d16_hi v179, v216, s[24:25] offset:64
	v_mul_f32_e32 v217, v209, v1
	v_bfe_u32 v253, v217, 16, 1
	v_add3_u32 v217, v217, v253, s76
	global_store_short_d16_hi v182, v217, s[24:25] offset:64
	v_mul_f32_e32 v214, v209, v6
	v_bfe_u32 v253, v214, 16, 1
	v_add3_u32 v214, v214, v253, s76
	global_store_short_d16_hi v179, v214, s[24:25] offset:128
	v_mul_f32_e32 v215, v209, v2
	v_bfe_u32 v253, v215, 16, 1
	v_add3_u32 v215, v215, v253, s76
	global_store_short_d16_hi v182, v215, s[24:25] offset:128
	v_mul_f32_e32 v216, v209, v7
	v_bfe_u32 v253, v216, 16, 1
	v_add3_u32 v216, v216, v253, s76
	global_store_short_d16_hi v179, v216, s[24:25] offset:192
	v_mul_f32_e32 v217, v209, v3
	v_bfe_u32 v253, v217, 16, 1
	v_add3_u32 v217, v217, v253, s76
	global_store_short_d16_hi v182, v217, s[24:25] offset:192
	s_mov_b64 s[2:3], exec
	s_branch .LBB0_306
